# adds: P3a 16-row hoist, P5 z prefetch, Wu 16-load hoist, pipelined x-loop (all loads issued ahead of stores)
# baseline (speedup 1.0000x reference)
; __device__ __forceinline__ void p0_prep(const Params& p, unsigned char* lds, int bid, int nb) {
;     ...
;   { bf16_t* xb = (bf16_t*)(ws + OFF_QL0); unsigned char* xq = ws + OFF_XQ; float* ss0 = (float*)(ws + OFF_SS);
;     for (int row = bid * 8 + wid; row < T; row += nb * 8) {
;       const f32x4* src = (const f32x4*)(p.x + (size_t)row * D); float s = 0.f;
; #pragma unroll
;       for (int j = 0; j < 8; ++j) { const f32x4 v = src[lane + 64 * j]; s += v[0] * v[0] + v[1] * v[1] + v[2] * v[2] + v[3] * v[3];
.LBB0_2:
	s_or_b64 exec, exec, s[4:5]
	s_lshl_b32 s4, s88, 3
	v_mov_b32_e32 v22, v200
	s_mov_b32 s2, s4
	v_writelane_b32 v254, s2, 22
	v_ashrrev_i32_e32 v2, 6, v22
	v_add_u32_e32 v12, s4, v2
	v_writelane_b32 v254, s3, 23
	s_mov_b32 s2, 0x8000
	v_and_b32_e32 v1, 63, v22
	v_cmp_gt_i32_e32 vcc, s2, v12
	s_and_saveexec_b64 s[6:7], vcc
	s_cbranch_execz .LBB0_7
	s_load_dwordx4 s[12:15], s[0:1], 0x80
	v_readlane_b32 s2, v254, 22
	v_ashrrev_i32_e32 v3, 31, v2
	s_mov_b32 s4, s2
	s_ashr_i32 s5, s2, 31
	v_readlane_b32 s3, v254, 23
	v_lshl_add_u64 v[10:11], v[2:3], 0, s[4:5]
	s_load_dwordx16 s[36:51], s[0:1], 0x0
	v_writelane_b32 v254, s2, 22
	v_lshlrev_b64 v[6:7], 11, v[10:11]
	s_waitcnt lgkmcnt(0)
	v_lshl_add_u64 v[4:5], v[10:11], 2, s[14:15]
	v_writelane_b32 v254, s3, 23
	s_mov_b64 s[2:3], 0x3eb00000
	v_lshl_or_b32 v6, v1, 2, v6
	v_lshlrev_b64 v[8:9], 12, v[10:11]
	v_lshl_add_u64 v[4:5], v[4:5], 0, s[2:3]
	v_lshl_add_u64 v[6:7], s[14:15], 0, v[6:7]
	s_mov_b64 s[2:3], 0x28000400
	v_lshl_or_b32 v8, v1, 3, v8
	v_lshlrev_b64 v[10:11], 13, v[10:11]
	s_lshl_b32 s8, s89, 3
	v_lshl_add_u64 v[6:7], v[6:7], 0, s[2:3]
	v_lshl_add_u64 v[8:9], s[14:15], 0, v[8:9]
	s_mov_b64 s[2:3], 0x20000800
	v_lshl_or_b32 v10, v1, 4, v10
	s_ashr_i32 s9, s8, 31
	v_lshl_add_u64 v[8:9], v[8:9], 0, s[2:3]
	v_lshl_add_u64 v[10:11], s[36:37], 0, v[10:11]
	s_mov_b64 s[2:3], 0x1000
	v_cmp_eq_u32_e32 vcc, 0, v1
	s_lshl_b64 s[10:11], s[8:9], 2
	s_lshl_b64 s[12:13], s[8:9], 11
	s_lshl_b64 s[14:15], s[8:9], 12
	v_lshl_add_u64 v[10:11], v[10:11], 0, s[2:3]
	s_lshl_b64 s[16:17], s[8:9], 13
	s_mov_b64 s[18:19], 0
	s_movk_i32 s2, 0x7fff
	global_load_dwordx4 v[14:17], v[10:11], off offset:-4096
	global_load_dwordx4 v[18:21], v[10:11], off offset:-3072
	global_load_dwordx4 v[24:27], v[10:11], off offset:-2048
	global_load_dwordx4 v[28:31], v[10:11], off offset:-1024
	global_load_dwordx4 v[32:35], v[10:11], off
	global_load_dwordx4 v[36:39], v[10:11], off offset:1024
	global_load_dwordx4 v[40:43], v[10:11], off offset:2048
	global_load_dwordx4 v[44:47], v[10:11], off offset:3072
	s_waitcnt vmcnt(0)
	s_branch .LBB0_5

; __device__ __forceinline__ unsigned cvt_pk_bf16(float lo, float hi) { unsigned r; asm("v_cvt_pk_bf16_f32 %0, %1, %2" : "=v"(r) : "v"(lo), "v"(hi)); return r; }
; __device__ __forceinline__ float wave_sum(float s, int) { s += dppf<0x128>(s); s += dppf<0x124>(s); s += dppf<0x122>(s); s += dppf<0x121>(s); return psum32(psum16(s)); }
; __device__ __forceinline__ void p0_prep(const Params& p, unsigned char* lds, int bid, int nb) {
;     ...
;     for (int row = bid * 8 + wid; row < T; row += nb * 8) {
;       const f32x4* src = (const f32x4*)(p.x + (size_t)row * D); float s = 0.f;
; #pragma unroll
;       for (int j = 0; j < 8; ++j) { const f32x4 v = src[lane + 64 * j]; s += v[0] * v[0] + v[1] * v[1] + v[2] * v[2] + v[3] * v[3];
;         u32x2 o; o[0] = cvt_pk_bf16(v[0], v[1]); o[1] = cvt_pk_bf16(v[2], v[3]); *(u32x2*)(xb + (size_t)row * D + (lane + 64 * j) * 4) = o;
;         unsigned q8 = __builtin_amdgcn_cvt_pk_fp8_f32(v[0], v[1], 0, false); q8 = __builtin_amdgcn_cvt_pk_fp8_f32(v[2], v[3], q8, true); *(unsigned*)(xq + (size_t)row * D + (lane + 64 * j) * 4) = q8; }
;       s = wave_sum(s, lane); if (lane == 0) ss0[row] = s;
;     }
.LBB0_5:
	s_waitcnt vmcnt(24)
	v_cvt_pk_bf16_f32 v56, v14, v15
	v_cvt_pk_bf16_f32 v57, v16, v17
	v_cvt_pk_fp8_f32 v72, v14, v15
	v_mul_f32_e32 v13, v15, v15
	v_fmac_f32_e32 v13, v14, v14
	v_fmac_f32_e32 v13, v16, v16
	v_cvt_pk_fp8_f32 v72, v16, v17 op_sel:[0,0,1]
	v_fmac_f32_e32 v13, v17, v17
	s_waitcnt vmcnt(23)
	v_cvt_pk_bf16_f32 v58, v18, v19
	v_cvt_pk_bf16_f32 v59, v20, v21
	v_cvt_pk_fp8_f32 v73, v18, v19
	v_mul_f32_e32 v14, v19, v19
	v_fmac_f32_e32 v14, v18, v18
	v_fmac_f32_e32 v14, v20, v20
	v_cvt_pk_fp8_f32 v73, v20, v21 op_sel:[0,0,1]
	v_fmac_f32_e32 v14, v21, v21
	v_add_f32_e32 v13, v13, v14
	s_waitcnt vmcnt(22)
	v_cvt_pk_bf16_f32 v60, v24, v25
	v_cvt_pk_bf16_f32 v61, v26, v27
	v_cvt_pk_fp8_f32 v74, v24, v25
	v_mul_f32_e32 v14, v25, v25
	v_fmac_f32_e32 v14, v24, v24
	v_fmac_f32_e32 v14, v26, v26
	v_cvt_pk_fp8_f32 v74, v26, v27 op_sel:[0,0,1]
	v_fmac_f32_e32 v14, v27, v27
	v_add_f32_e32 v13, v13, v14
	s_waitcnt vmcnt(21)
	v_cvt_pk_bf16_f32 v62, v28, v29
	v_cvt_pk_bf16_f32 v63, v30, v31
	v_cvt_pk_fp8_f32 v75, v28, v29
	v_mul_f32_e32 v14, v29, v29
	v_fmac_f32_e32 v14, v28, v28
	v_fmac_f32_e32 v14, v30, v30
	v_cvt_pk_fp8_f32 v75, v30, v31 op_sel:[0,0,1]
	v_fmac_f32_e32 v14, v31, v31
	v_add_f32_e32 v13, v13, v14
	s_waitcnt vmcnt(20)
	v_cvt_pk_bf16_f32 v64, v32, v33
	v_cvt_pk_bf16_f32 v65, v34, v35
	v_cvt_pk_fp8_f32 v76, v32, v33
	v_mul_f32_e32 v14, v33, v33
	v_fmac_f32_e32 v14, v32, v32
	v_fmac_f32_e32 v14, v34, v34
	v_cvt_pk_fp8_f32 v76, v34, v35 op_sel:[0,0,1]
	v_fmac_f32_e32 v14, v35, v35
	v_add_f32_e32 v13, v13, v14
	s_waitcnt vmcnt(19)
	v_cvt_pk_bf16_f32 v66, v36, v37
	v_cvt_pk_bf16_f32 v67, v38, v39
	v_cvt_pk_fp8_f32 v77, v36, v37
	v_mul_f32_e32 v14, v37, v37
	v_fmac_f32_e32 v14, v36, v36
	v_fmac_f32_e32 v14, v38, v38
	v_cvt_pk_fp8_f32 v77, v38, v39 op_sel:[0,0,1]
	v_fmac_f32_e32 v14, v39, v39
	v_add_f32_e32 v13, v13, v14
	s_waitcnt vmcnt(18)
	v_cvt_pk_bf16_f32 v68, v40, v41
	v_cvt_pk_bf16_f32 v69, v42, v43
	v_cvt_pk_fp8_f32 v78, v40, v41
	v_mul_f32_e32 v14, v41, v41
	v_fmac_f32_e32 v14, v40, v40
	v_fmac_f32_e32 v14, v42, v42
	v_cvt_pk_fp8_f32 v78, v42, v43 op_sel:[0,0,1]
	v_fmac_f32_e32 v14, v43, v43
	v_add_f32_e32 v13, v13, v14
	s_waitcnt vmcnt(17)
	v_cvt_pk_bf16_f32 v70, v44, v45
	v_cvt_pk_bf16_f32 v71, v46, v47
	v_cvt_pk_fp8_f32 v79, v44, v45
	v_mul_f32_e32 v16, v45, v45
	v_fmac_f32_e32 v16, v44, v44
	v_fmac_f32_e32 v16, v46, v46
	v_cvt_pk_fp8_f32 v79, v46, v47 op_sel:[0,0,1]
	v_fmac_f32_e32 v16, v47, v47
	v_add_f32_e32 v13, v13, v16
	v_add_u32_e32 v80, s8, v12
	v_cmp_lt_i32_e64 s[4:5], s2, v80
	v_lshl_add_u64 v[82:83], v[10:11], 0, s[16:17]
	s_nop 1
	s_and_b64 s[4:5], s[4:5], exec
	s_cbranch_scc1 .Lx_nopf
	global_load_dwordx4 v[14:17], v[82:83], off offset:-4096
	global_load_dwordx4 v[18:21], v[82:83], off offset:-3072
	global_load_dwordx4 v[24:27], v[82:83], off offset:-2048
	global_load_dwordx4 v[28:31], v[82:83], off offset:-1024
	global_load_dwordx4 v[32:35], v[82:83], off
	global_load_dwordx4 v[36:39], v[82:83], off offset:1024
	global_load_dwordx4 v[40:43], v[82:83], off offset:2048
	global_load_dwordx4 v[44:47], v[82:83], off offset:3072
.Lx_nopf:
	global_store_dwordx2 v[8:9], v[56:57], off offset:-2048
	global_store_dword v[6:7], v72, off offset:-1024
	global_store_dwordx2 v[8:9], v[58:59], off offset:-1536
	global_store_dword v[6:7], v73, off offset:-768
	global_store_dwordx2 v[8:9], v[60:61], off offset:-1024
	global_store_dword v[6:7], v74, off offset:-512
	global_store_dwordx2 v[8:9], v[62:63], off offset:-512
	global_store_dword v[6:7], v75, off offset:-256
	global_store_dwordx2 v[8:9], v[64:65], off
	global_store_dword v[6:7], v76, off
	global_store_dwordx2 v[8:9], v[66:67], off offset:512
	global_store_dword v[6:7], v77, off offset:256
	global_store_dwordx2 v[8:9], v[68:69], off offset:1024
	global_store_dword v[6:7], v78, off offset:512
	global_store_dwordx2 v[8:9], v[70:71], off offset:1536
	global_store_dword v[6:7], v79, off offset:768
	v_add_f32_dpp v13, v13, v13 row_ror:8 row_mask:0xf bank_mask:0xf bound_ctrl:1
	s_nop 1
	v_add_f32_dpp v13, v13, v13 row_ror:4 row_mask:0xf bank_mask:0xf bound_ctrl:1
	s_nop 1
	v_add_f32_dpp v13, v13, v13 row_ror:2 row_mask:0xf bank_mask:0xf bound_ctrl:1
	s_nop 1
	v_add_f32_dpp v3, v13, v13 row_ror:1 row_mask:0xf bank_mask:0xf bound_ctrl:1
	v_mov_b32_e32 v13, v3
	s_nop 1
	v_permlane16_swap_b32_e32 v3, v13
	v_add_f32_e32 v3, v3, v13
	v_mov_b32_e32 v13, v3
	s_nop 1
	v_permlane32_swap_b32_e32 v3, v13
	s_and_saveexec_b64 s[4:5], vcc
	s_cbranch_execz .LBB0_4
	v_add_f32_e32 v3, v3, v13
	global_store_dword v[4:5], v3, off
	s_branch .LBB0_4

; __device__ __forceinline__ unsigned cvt_pk_bf16(float lo, float hi) { unsigned r; asm("v_cvt_pk_bf16_f32 %0, %1, %2" : "=v"(r) : "v"(lo), "v"(hi)); return r; }
; __device__ __forceinline__ void p0_prep(const Params& p, unsigned char* lds, int bid, int nb) {
;     ...
;     bf16_t* wu = (bf16_t*)(ws + OFF_WU);
;     for (int i = bid * 512 + tid; i < 4 * 2048 * 256; i += nb * 512) {
;       const int p4 = i & 255, k = (i >> 8) & 2047, g = i >> 19;
;       const f32x4 v = *(const f32x4*)(p.w_in_b + (size_t)k * 8192 + g * 1024 + p4 * 4) * p.norm_b[k];
;       u32x2 o; o[0] = cvt_pk_bf16(v[0], v[1]); o[1] = cvt_pk_bf16(v[2], v[3]); *(u32x2*)(wu + (size_t)g * 2097152 + (size_t)k * 1024 + p4 * 4) = o;
;     } }
.LBB0_354:
	v_writelane_b32 v254, s8, 28
	s_nop 1
	v_writelane_b32 v254, s9, 29
	s_or_b64 exec, exec, s[0:1]
	v_readlane_b32 s0, v254, 16
	v_readlane_b32 s2, v254, 18
	v_readlane_b32 s1, v254, 17
	v_readlane_b32 s3, v254, 19
	s_add_u32 s0, s2, 0x33100000
	s_mov_b32 s2, 0x200000
	s_addc_u32 s1, s3, 0
	v_cmp_gt_i32_e32 vcc, s2, v4
	v_lshlrev_b32_e32 v5, 2, v22
	s_and_saveexec_b64 s[4:5], vcc
	s_cbranch_execz .LBB0_357
	s_lshl_b32 s2, s89, 9
	v_lshl_add_u32 v7, s88, 11, v5
	s_lshl_b32 s3, s89, 11
	s_mov_b64 s[6:7], 0
	v_mov_b32_e32 v3, 0
	s_mov_b32 s8, 0x1fffff
	v_mov_b32_e32 v8, v4
	s_cmp_lg_u32 s89, 0x100
	s_cbranch_scc1 .LBB0_356
	v_bfe_u32 v9, v8, 8, 11
	v_ashrrev_i32_e32 v14, 19, v8
	v_lshlrev_b32_e32 v2, 15, v9
	v_lshlrev_b32_e32 v10, 10, v14
	v_and_b32_e32 v17, 0x3fc, v7
	v_lshl_add_u64 v[12:13], s[14:15], 0, v[2:3]
	v_ashrrev_i32_e32 v11, 31, v10
	v_lshlrev_b32_e32 v2, 2, v17
	v_lshl_add_u64 v[10:11], v[10:11], 2, v[12:13]
	v_lshlrev_b32_e32 v15, 2, v9
	v_lshl_add_u64 v[10:11], v[10:11], 0, v[2:3]
	global_load_dword v164, v15, s[12:13]
	global_load_dword v165, v15, s[12:13] offset:2048
	v_add_u32_e32 v96, 0x1000, v15
	global_load_dword v166, v96, s[12:13]
	global_load_dword v167, v96, s[12:13] offset:2048
	global_load_dwordx4 v[100:103], v[10:11], off
	s_mov_b64 s[74:75], 0x1000000
	v_lshl_add_u64 v[96:97], v[10:11], 0, s[74:75]
	global_load_dwordx4 v[104:107], v[96:97], off
	s_mov_b64 s[74:75], 0x2000000
	v_lshl_add_u64 v[98:99], v[10:11], 0, s[74:75]
	global_load_dwordx4 v[108:111], v[98:99], off
	s_mov_b64 s[74:75], 0x3000000
	v_lshl_add_u64 v[96:97], v[10:11], 0, s[74:75]
	global_load_dwordx4 v[112:115], v[96:97], off
	s_mov_b64 s[74:75], 0x1000
	v_lshl_add_u64 v[98:99], v[10:11], 0, s[74:75]
	global_load_dwordx4 v[116:119], v[98:99], off
	s_mov_b64 s[74:75], 0x1001000
	v_lshl_add_u64 v[96:97], v[10:11], 0, s[74:75]
	global_load_dwordx4 v[120:123], v[96:97], off
	s_mov_b64 s[74:75], 0x2001000
	v_lshl_add_u64 v[98:99], v[10:11], 0, s[74:75]
	global_load_dwordx4 v[124:127], v[98:99], off
	s_mov_b64 s[74:75], 0x3001000
	v_lshl_add_u64 v[96:97], v[10:11], 0, s[74:75]
	global_load_dwordx4 v[128:131], v[96:97], off
	s_mov_b64 s[74:75], 0x2000
	v_lshl_add_u64 v[98:99], v[10:11], 0, s[74:75]
	global_load_dwordx4 v[132:135], v[98:99], off
	s_mov_b64 s[74:75], 0x1002000
	v_lshl_add_u64 v[96:97], v[10:11], 0, s[74:75]
	global_load_dwordx4 v[136:139], v[96:97], off
	s_mov_b64 s[74:75], 0x2002000
	v_lshl_add_u64 v[98:99], v[10:11], 0, s[74:75]
	global_load_dwordx4 v[140:143], v[98:99], off
	s_mov_b64 s[74:75], 0x3002000
	v_lshl_add_u64 v[96:97], v[10:11], 0, s[74:75]
	global_load_dwordx4 v[144:147], v[96:97], off
	s_mov_b64 s[74:75], 0x3000
	v_lshl_add_u64 v[98:99], v[10:11], 0, s[74:75]
	global_load_dwordx4 v[148:151], v[98:99], off
	s_mov_b64 s[74:75], 0x1003000
	v_lshl_add_u64 v[96:97], v[10:11], 0, s[74:75]
	global_load_dwordx4 v[152:155], v[96:97], off
	s_mov_b64 s[74:75], 0x2003000
	v_lshl_add_u64 v[98:99], v[10:11], 0, s[74:75]
	global_load_dwordx4 v[156:159], v[98:99], off
	s_mov_b64 s[74:75], 0x3003000
	v_lshl_add_u64 v[96:97], v[10:11], 0, s[74:75]
	global_load_dwordx4 v[160:163], v[96:97], off
	v_ashrrev_i32_e32 v15, 31, v14
	v_lshlrev_b64 v[14:15], 22, v[14:15]
	v_lshl_add_u64 v[14:15], s[0:1], 0, v[14:15]
	v_lshlrev_b32_e32 v2, 11, v9
	v_lshl_add_u64 v[14:15], v[14:15], 0, v[2:3]
	v_lshlrev_b32_e32 v2, 1, v17
	v_lshl_add_u64 v[14:15], v[14:15], 0, v[2:3]
	s_waitcnt vmcnt(15)
	v_mul_f32_e32 v100, v164, v100
	v_mul_f32_e32 v101, v164, v101
	v_mul_f32_e32 v102, v164, v102
	v_mul_f32_e32 v103, v164, v103
	v_cvt_pk_bf16_f32 v100, v100, v101
	v_cvt_pk_bf16_f32 v101, v102, v103
	s_waitcnt vmcnt(14)
	v_mul_f32_e32 v104, v165, v104
	v_mul_f32_e32 v105, v165, v105
	v_mul_f32_e32 v106, v165, v106
	v_mul_f32_e32 v107, v165, v107
	v_cvt_pk_bf16_f32 v104, v104, v105
	v_cvt_pk_bf16_f32 v105, v106, v107
	s_waitcnt vmcnt(13)
	v_mul_f32_e32 v108, v166, v108
	v_mul_f32_e32 v109, v166, v109
	v_mul_f32_e32 v110, v166, v110
	v_mul_f32_e32 v111, v166, v111
	v_cvt_pk_bf16_f32 v108, v108, v109
	v_cvt_pk_bf16_f32 v109, v110, v111
	s_waitcnt vmcnt(12)
	v_mul_f32_e32 v112, v167, v112
	v_mul_f32_e32 v113, v167, v113
	v_mul_f32_e32 v114, v167, v114
	v_mul_f32_e32 v115, v167, v115
	v_cvt_pk_bf16_f32 v112, v112, v113
	v_cvt_pk_bf16_f32 v113, v114, v115
	s_waitcnt vmcnt(11)
	v_mul_f32_e32 v116, v164, v116
	v_mul_f32_e32 v117, v164, v117
	v_mul_f32_e32 v118, v164, v118
	v_mul_f32_e32 v119, v164, v119
	v_cvt_pk_bf16_f32 v116, v116, v117
	v_cvt_pk_bf16_f32 v117, v118, v119
	s_waitcnt vmcnt(10)
; __device__ __forceinline__ unsigned cvt_pk_bf16(float lo, float hi) { unsigned r; asm("v_cvt_pk_bf16_f32 %0, %1, %2" : "=v"(r) : "v"(lo), "v"(hi)); return r; }
; __device__ __forceinline__ void p0_prep(const Params& p, unsigned char* lds, int bid, int nb) {
;     ...
;     bf16_t* wu = (bf16_t*)(ws + OFF_WU);
;     for (int i = bid * 512 + tid; i < 4 * 2048 * 256; i += nb * 512) {
;       const int p4 = i & 255, k = (i >> 8) & 2047, g = i >> 19;
;       const f32x4 v = *(const f32x4*)(p.w_in_b + (size_t)k * 8192 + g * 1024 + p4 * 4) * p.norm_b[k];
;       u32x2 o; o[0] = cvt_pk_bf16(v[0], v[1]); o[1] = cvt_pk_bf16(v[2], v[3]); *(u32x2*)(wu + (size_t)g * 2097152 + (size_t)k * 1024 + p4 * 4) = o;
;     } }
	v_mul_f32_e32 v120, v165, v120
	v_mul_f32_e32 v121, v165, v121
	v_mul_f32_e32 v122, v165, v122
	v_mul_f32_e32 v123, v165, v123
	v_cvt_pk_bf16_f32 v120, v120, v121
	v_cvt_pk_bf16_f32 v121, v122, v123
	s_waitcnt vmcnt(9)
	v_mul_f32_e32 v124, v166, v124
	v_mul_f32_e32 v125, v166, v125
	v_mul_f32_e32 v126, v166, v126
	v_mul_f32_e32 v127, v166, v127
	v_cvt_pk_bf16_f32 v124, v124, v125
	v_cvt_pk_bf16_f32 v125, v126, v127
	s_waitcnt vmcnt(8)
	v_mul_f32_e32 v128, v167, v128
	v_mul_f32_e32 v129, v167, v129
	v_mul_f32_e32 v130, v167, v130
	v_mul_f32_e32 v131, v167, v131
	v_cvt_pk_bf16_f32 v128, v128, v129
	v_cvt_pk_bf16_f32 v129, v130, v131
	s_waitcnt vmcnt(7)
	v_mul_f32_e32 v132, v164, v132
	v_mul_f32_e32 v133, v164, v133
	v_mul_f32_e32 v134, v164, v134
	v_mul_f32_e32 v135, v164, v135
	v_cvt_pk_bf16_f32 v132, v132, v133
	v_cvt_pk_bf16_f32 v133, v134, v135
	s_waitcnt vmcnt(6)
	v_mul_f32_e32 v136, v165, v136
	v_mul_f32_e32 v137, v165, v137
	v_mul_f32_e32 v138, v165, v138
	v_mul_f32_e32 v139, v165, v139
	v_cvt_pk_bf16_f32 v136, v136, v137
	v_cvt_pk_bf16_f32 v137, v138, v139
	s_waitcnt vmcnt(5)
	v_mul_f32_e32 v140, v166, v140
	v_mul_f32_e32 v141, v166, v141
	v_mul_f32_e32 v142, v166, v142
	v_mul_f32_e32 v143, v166, v143
	v_cvt_pk_bf16_f32 v140, v140, v141
	v_cvt_pk_bf16_f32 v141, v142, v143
	s_waitcnt vmcnt(4)
	v_mul_f32_e32 v144, v167, v144
	v_mul_f32_e32 v145, v167, v145
	v_mul_f32_e32 v146, v167, v146
	v_mul_f32_e32 v147, v167, v147
	v_cvt_pk_bf16_f32 v144, v144, v145
	v_cvt_pk_bf16_f32 v145, v146, v147
	s_waitcnt vmcnt(3)
	v_mul_f32_e32 v148, v164, v148
	v_mul_f32_e32 v149, v164, v149
	v_mul_f32_e32 v150, v164, v150
	v_mul_f32_e32 v151, v164, v151
	v_cvt_pk_bf16_f32 v148, v148, v149
	v_cvt_pk_bf16_f32 v149, v150, v151
	s_waitcnt vmcnt(2)
	v_mul_f32_e32 v152, v165, v152
	v_mul_f32_e32 v153, v165, v153
	v_mul_f32_e32 v154, v165, v154
	v_mul_f32_e32 v155, v165, v155
	v_cvt_pk_bf16_f32 v152, v152, v153
	v_cvt_pk_bf16_f32 v153, v154, v155
	s_waitcnt vmcnt(1)
	v_mul_f32_e32 v156, v166, v156
	v_mul_f32_e32 v157, v166, v157
	v_mul_f32_e32 v158, v166, v158
	v_mul_f32_e32 v159, v166, v159
	v_cvt_pk_bf16_f32 v156, v156, v157
	v_cvt_pk_bf16_f32 v157, v158, v159
	s_waitcnt vmcnt(0)
	v_mul_f32_e32 v160, v167, v160
	v_mul_f32_e32 v161, v167, v161
	v_mul_f32_e32 v162, v167, v162
	v_mul_f32_e32 v163, v167, v163
	v_cvt_pk_bf16_f32 v160, v160, v161
	v_cvt_pk_bf16_f32 v161, v162, v163
	global_store_dwordx2 v[14:15], v[100:101], off
	s_mov_b64 s[74:75], 0x100000
	v_lshl_add_u64 v[96:97], v[14:15], 0, s[74:75]
	global_store_dwordx2 v[96:97], v[104:105], off
	s_mov_b64 s[74:75], 0x200000
	v_lshl_add_u64 v[98:99], v[14:15], 0, s[74:75]
	global_store_dwordx2 v[98:99], v[108:109], off
	s_mov_b64 s[74:75], 0x300000
	v_lshl_add_u64 v[96:97], v[14:15], 0, s[74:75]
	global_store_dwordx2 v[96:97], v[112:113], off
	s_mov_b64 s[74:75], 0x400000
	v_lshl_add_u64 v[98:99], v[14:15], 0, s[74:75]
	global_store_dwordx2 v[98:99], v[116:117], off
	s_mov_b64 s[74:75], 0x500000
	v_lshl_add_u64 v[96:97], v[14:15], 0, s[74:75]
	global_store_dwordx2 v[96:97], v[120:121], off
	s_mov_b64 s[74:75], 0x600000
	v_lshl_add_u64 v[98:99], v[14:15], 0, s[74:75]
	global_store_dwordx2 v[98:99], v[124:125], off
	s_mov_b64 s[74:75], 0x700000
	v_lshl_add_u64 v[96:97], v[14:15], 0, s[74:75]
	global_store_dwordx2 v[96:97], v[128:129], off
	s_mov_b64 s[74:75], 0x800000
	v_lshl_add_u64 v[98:99], v[14:15], 0, s[74:75]
	global_store_dwordx2 v[98:99], v[132:133], off
	s_mov_b64 s[74:75], 0x900000
	v_lshl_add_u64 v[96:97], v[14:15], 0, s[74:75]
	global_store_dwordx2 v[96:97], v[136:137], off
	s_mov_b64 s[74:75], 0xa00000
	v_lshl_add_u64 v[98:99], v[14:15], 0, s[74:75]
	global_store_dwordx2 v[98:99], v[140:141], off
	s_mov_b64 s[74:75], 0xb00000
	v_lshl_add_u64 v[96:97], v[14:15], 0, s[74:75]
	global_store_dwordx2 v[96:97], v[144:145], off
	s_mov_b64 s[74:75], 0xc00000
	v_lshl_add_u64 v[98:99], v[14:15], 0, s[74:75]
	global_store_dwordx2 v[98:99], v[148:149], off
	s_mov_b64 s[74:75], 0xd00000
	v_lshl_add_u64 v[96:97], v[14:15], 0, s[74:75]
	global_store_dwordx2 v[96:97], v[152:153], off
	s_mov_b64 s[74:75], 0xe00000
	v_lshl_add_u64 v[98:99], v[14:15], 0, s[74:75]
	global_store_dwordx2 v[98:99], v[156:157], off
	s_mov_b64 s[74:75], 0xf00000
	v_lshl_add_u64 v[96:97], v[14:15], 0, s[74:75]
	global_store_dwordx2 v[96:97], v[160:161], off
	s_branch .LBB0_357

; __device__ __forceinline__ unsigned cvt_pk_bf16(float lo, float hi) { unsigned r; asm("v_cvt_pk_bf16_f32 %0, %1, %2" : "=v"(r) : "v"(lo), "v"(hi)); return r; }
; __device__ __forceinline__ float wave_sum(float s, int) { s += dppf<0x128>(s); s += dppf<0x124>(s); s += dppf<0x122>(s); s += dppf<0x121>(s); return psum32(psum16(s)); }
; __device__ __forceinline__ void p3_ckvnorm(const Params& p, int bid, int nb) {
;   int tid = threadIdx.x; asm volatile("" : "+v"(tid));
;   const int lane = tid & 63, wid = tid >> 6;
;   const float* cr = (const float*)(p.ws + OFF_CKVR); bf16_t* cn = (bf16_t*)(p.ws + OFF_CKVN);
;   const f32x4 g = *(const f32x4*)((const float*)(p.ws + OFF_SMALL) + SM_KVN + lane * 4);
;   for (int row = bid * 8 + wid; row < T; row += nb * 8) {
;     const f32x4 v = *(const f32x4*)(cr + (size_t)row * 256 + lane * 4);
;     float s = v[0] * v[0] + v[1] * v[1] + v[2] * v[2] + v[3] * v[3]; s = wave_sum(s, lane);
;     const float r = rsqrtf(s * (1.f / 256.f) + EPS);
;     u32x2 o; o[0] = cvt_pk_bf16(v[0] * r * g[0], v[1] * r * g[1]); o[1] = cvt_pk_bf16(v[2] * r * g[2], v[3] * r * g[3]);
;     *(u32x2*)(cn + (size_t)row * 256 + lane * 4) = o;
.LBB0_942:
	v_mov_b32_e32 v6, v200
	s_waitcnt vmcnt(63) expcnt(7) lgkmcnt(15)
	s_barrier
	v_readlane_b32 s0, v254, 22
	v_ashrrev_i32_e32 v4, 6, v6
	v_readlane_b32 s1, v254, 23
	v_add_u32_e32 v8, s0, v4
	s_mov_b32 s0, 0x8000
	v_cmp_gt_i32_e32 vcc, s0, v8
	s_and_saveexec_b64 s[4:5], vcc
	s_cbranch_execz .LBB0_945
	v_lshlrev_b32_e32 v0, 4, v6
	v_readlane_b32 s0, v254, 16
	v_and_b32_e32 v0, 0x3f0, v0
	v_mov_b32_e32 v1, 0
	v_readlane_b32 s2, v254, 18
	v_readlane_b32 s3, v254, 19
	v_readlane_b32 s1, v254, 17
	v_readlane_b32 s0, v254, 22
	v_lshl_add_u64 v[0:1], s[2:3], 0, v[0:1]
	v_add_co_u32_e32 v0, vcc, 0x3eb60000, v0
	v_ashrrev_i32_e32 v5, 31, v4
	s_nop 0
	v_addc_co_u32_e32 v1, vcc, 0, v1, vcc
	global_load_dwordx4 v[0:3], v[0:1], off offset:512
	s_mov_b32 s8, s0
	s_ashr_i32 s9, s0, 31
	v_lshl_add_u64 v[10:11], v[4:5], 0, s[8:9]
	v_readlane_b32 s1, v254, 23
	v_lshlrev_b64 v[4:5], 10, v[10:11]
	v_and_b32_e32 v9, 63, v6
	v_writelane_b32 v254, s0, 22
	v_lshl_or_b32 v4, v9, 4, v4
	v_lshlrev_b64 v[6:7], 9, v[10:11]
	s_lshl_b32 s6, s89, 3
	v_writelane_b32 v254, s1, 23
	v_lshl_add_u64 v[4:5], s[2:3], 0, v[4:5]
	s_mov_b64 s[0:1], 0x38500000
	v_lshl_or_b32 v6, v9, 3, v6
	v_lshl_add_u64 v[4:5], v[4:5], 0, s[0:1]
	s_ashr_i32 s7, s6, 31
	v_lshl_add_u64 v[6:7], s[2:3], 0, v[6:7]
	s_mov_b64 s[0:1], 0x36f00000
	s_lshl_b64 s[8:9], s[6:7], 10
	v_lshl_add_u64 v[6:7], v[6:7], 0, s[0:1]
	s_lshl_b64 s[10:11], s[6:7], 9
	s_mov_b64 s[12:13], 0
	v_mov_b32_e32 v9, 0x358637bd
	s_mov_b32 s0, 0x800000
	s_movk_i32 s1, 0x7fff
	s_cmp_lg_u32 s89, 0x100
	s_cbranch_scc1 .LBB0_944
	global_load_dwordx4 v[20:23], v[4:5], off
	v_lshl_add_u64 v[4:5], v[4:5], 0, s[8:9]
	global_load_dwordx4 v[24:27], v[4:5], off
	v_lshl_add_u64 v[4:5], v[4:5], 0, s[8:9]
	global_load_dwordx4 v[28:31], v[4:5], off
	v_lshl_add_u64 v[4:5], v[4:5], 0, s[8:9]
	global_load_dwordx4 v[32:35], v[4:5], off
	v_lshl_add_u64 v[4:5], v[4:5], 0, s[8:9]
	global_load_dwordx4 v[36:39], v[4:5], off
	v_lshl_add_u64 v[4:5], v[4:5], 0, s[8:9]
	global_load_dwordx4 v[40:43], v[4:5], off
	v_lshl_add_u64 v[4:5], v[4:5], 0, s[8:9]
	global_load_dwordx4 v[44:47], v[4:5], off
	v_lshl_add_u64 v[4:5], v[4:5], 0, s[8:9]
	global_load_dwordx4 v[48:51], v[4:5], off
	v_lshl_add_u64 v[4:5], v[4:5], 0, s[8:9]
	global_load_dwordx4 v[52:55], v[4:5], off
	v_lshl_add_u64 v[4:5], v[4:5], 0, s[8:9]
	global_load_dwordx4 v[56:59], v[4:5], off
	v_lshl_add_u64 v[4:5], v[4:5], 0, s[8:9]
	global_load_dwordx4 v[60:63], v[4:5], off
	v_lshl_add_u64 v[4:5], v[4:5], 0, s[8:9]
	global_load_dwordx4 v[64:67], v[4:5], off
	v_lshl_add_u64 v[4:5], v[4:5], 0, s[8:9]
	global_load_dwordx4 v[68:71], v[4:5], off
	v_lshl_add_u64 v[4:5], v[4:5], 0, s[8:9]
	global_load_dwordx4 v[72:75], v[4:5], off
	v_lshl_add_u64 v[4:5], v[4:5], 0, s[8:9]
	global_load_dwordx4 v[76:79], v[4:5], off
	v_lshl_add_u64 v[4:5], v[4:5], 0, s[8:9]
	global_load_dwordx4 v[80:83], v[4:5], off
	s_waitcnt vmcnt(15)
	v_mul_f32_e32 v14, v21, v21
	v_fmac_f32_e32 v14, v20, v20
	v_fmac_f32_e32 v14, v22, v22
	v_fmac_f32_e32 v14, v23, v23
	s_nop 1
	v_add_f32_dpp v14, v14, v14 row_ror:8 row_mask:0xf bank_mask:0xf bound_ctrl:1
	s_nop 1
	v_add_f32_dpp v14, v14, v14 row_ror:4 row_mask:0xf bank_mask:0xf bound_ctrl:1
	s_nop 1
	v_add_f32_dpp v14, v14, v14 row_ror:2 row_mask:0xf bank_mask:0xf bound_ctrl:1
	s_nop 1
	v_add_f32_dpp v14, v14, v14 row_ror:1 row_mask:0xf bank_mask:0xf bound_ctrl:1
	v_mov_b32_e32 v15, v14
	s_nop 1
	v_permlane16_swap_b32_e32 v14, v15
	v_add_f32_e32 v14, v14, v15
	v_mov_b32_e32 v15, v14
	s_nop 1
	v_permlane32_swap_b32_e32 v14, v15
	v_add_f32_e32 v14, v14, v15
	v_fmamk_f32 v14, v14, 0x3b800000, v9
	v_mul_f32_e32 v15, 0x4b800000, v14
	v_cmp_gt_f32_e32 vcc, s0, v14
	s_nop 1
	v_cndmask_b32_e32 v14, v14, v15, vcc
	v_rsq_f32_e32 v14, v14
	s_nop 0
	v_mul_f32_e32 v15, 0x45800000, v14
	v_cndmask_b32_e32 v14, v14, v15, vcc
	v_mul_f32_e32 v20, v20, v14
	v_mul_f32_e32 v21, v21, v14
	v_mul_f32_e32 v22, v22, v14
	v_mul_f32_e32 v23, v23, v14
	v_mul_f32_e32 v20, v0, v20
	v_mul_f32_e32 v21, v1, v21
	v_mul_f32_e32 v22, v2, v22
	v_mul_f32_e32 v23, v3, v23
	v_cvt_pk_bf16_f32 v20, v20, v21
	v_cvt_pk_bf16_f32 v21, v22, v23
	s_waitcnt vmcnt(14)
	v_mul_f32_e32 v14, v25, v25
	v_fmac_f32_e32 v14, v24, v24
	v_fmac_f32_e32 v14, v26, v26
	v_fmac_f32_e32 v14, v27, v27
	s_nop 1
	v_add_f32_dpp v14, v14, v14 row_ror:8 row_mask:0xf bank_mask:0xf bound_ctrl:1
	s_nop 1
	v_add_f32_dpp v14, v14, v14 row_ror:4 row_mask:0xf bank_mask:0xf bound_ctrl:1
	s_nop 1
	v_add_f32_dpp v14, v14, v14 row_ror:2 row_mask:0xf bank_mask:0xf bound_ctrl:1
	s_nop 1
	v_add_f32_dpp v14, v14, v14 row_ror:1 row_mask:0xf bank_mask:0xf bound_ctrl:1
	v_mov_b32_e32 v15, v14
	s_nop 1
	v_permlane16_swap_b32_e32 v14, v15
	v_add_f32_e32 v14, v14, v15
	v_mov_b32_e32 v15, v14
	s_nop 1
	v_permlane32_swap_b32_e32 v14, v15
	v_add_f32_e32 v14, v14, v15
	v_fmamk_f32 v14, v14, 0x3b800000, v9
	v_mul_f32_e32 v15, 0x4b800000, v14
	v_cmp_gt_f32_e32 vcc, s0, v14
	s_nop 1
	v_cndmask_b32_e32 v14, v14, v15, vcc
	v_rsq_f32_e32 v14, v14
	s_nop 0
	v_mul_f32_e32 v15, 0x45800000, v14
	v_cndmask_b32_e32 v14, v14, v15, vcc
	v_mul_f32_e32 v24, v24, v14
	v_mul_f32_e32 v25, v25, v14
	v_mul_f32_e32 v26, v26, v14
	v_mul_f32_e32 v27, v27, v14
	v_mul_f32_e32 v24, v0, v24
	v_mul_f32_e32 v25, v1, v25
	v_mul_f32_e32 v26, v2, v26
	v_mul_f32_e32 v27, v3, v27
	v_cvt_pk_bf16_f32 v24, v24, v25
	v_cvt_pk_bf16_f32 v25, v26, v27
	s_waitcnt vmcnt(13)
; __device__ __forceinline__ unsigned cvt_pk_bf16(float lo, float hi) { unsigned r; asm("v_cvt_pk_bf16_f32 %0, %1, %2" : "=v"(r) : "v"(lo), "v"(hi)); return r; }
; __device__ __forceinline__ float wave_sum(float s, int) { s += dppf<0x128>(s); s += dppf<0x124>(s); s += dppf<0x122>(s); s += dppf<0x121>(s); return psum32(psum16(s)); }
; __device__ __forceinline__ void p3_ckvnorm(const Params& p, int bid, int nb) {
;     ...
;   for (int row = bid * 8 + wid; row < T; row += nb * 8) {
;     const f32x4 v = *(const f32x4*)(cr + (size_t)row * 256 + lane * 4);
;     float s = v[0] * v[0] + v[1] * v[1] + v[2] * v[2] + v[3] * v[3]; s = wave_sum(s, lane);
;     const float r = rsqrtf(s * (1.f / 256.f) + EPS);
;     u32x2 o; o[0] = cvt_pk_bf16(v[0] * r * g[0], v[1] * r * g[1]); o[1] = cvt_pk_bf16(v[2] * r * g[2], v[3] * r * g[3]);
;     *(u32x2*)(cn + (size_t)row * 256 + lane * 4) = o;
	v_mul_f32_e32 v14, v29, v29
	v_fmac_f32_e32 v14, v28, v28
	v_fmac_f32_e32 v14, v30, v30
	v_fmac_f32_e32 v14, v31, v31
	s_nop 1
	v_add_f32_dpp v14, v14, v14 row_ror:8 row_mask:0xf bank_mask:0xf bound_ctrl:1
	s_nop 1
	v_add_f32_dpp v14, v14, v14 row_ror:4 row_mask:0xf bank_mask:0xf bound_ctrl:1
	s_nop 1
	v_add_f32_dpp v14, v14, v14 row_ror:2 row_mask:0xf bank_mask:0xf bound_ctrl:1
	s_nop 1
	v_add_f32_dpp v14, v14, v14 row_ror:1 row_mask:0xf bank_mask:0xf bound_ctrl:1
	v_mov_b32_e32 v15, v14
	s_nop 1
	v_permlane16_swap_b32_e32 v14, v15
	v_add_f32_e32 v14, v14, v15
	v_mov_b32_e32 v15, v14
	s_nop 1
	v_permlane32_swap_b32_e32 v14, v15
	v_add_f32_e32 v14, v14, v15
	v_fmamk_f32 v14, v14, 0x3b800000, v9
	v_mul_f32_e32 v15, 0x4b800000, v14
	v_cmp_gt_f32_e32 vcc, s0, v14
	s_nop 1
	v_cndmask_b32_e32 v14, v14, v15, vcc
	v_rsq_f32_e32 v14, v14
	s_nop 0
	v_mul_f32_e32 v15, 0x45800000, v14
	v_cndmask_b32_e32 v14, v14, v15, vcc
	v_mul_f32_e32 v28, v28, v14
	v_mul_f32_e32 v29, v29, v14
	v_mul_f32_e32 v30, v30, v14
	v_mul_f32_e32 v31, v31, v14
	v_mul_f32_e32 v28, v0, v28
	v_mul_f32_e32 v29, v1, v29
	v_mul_f32_e32 v30, v2, v30
	v_mul_f32_e32 v31, v3, v31
	v_cvt_pk_bf16_f32 v28, v28, v29
	v_cvt_pk_bf16_f32 v29, v30, v31
	s_waitcnt vmcnt(12)
	v_mul_f32_e32 v14, v33, v33
	v_fmac_f32_e32 v14, v32, v32
	v_fmac_f32_e32 v14, v34, v34
	v_fmac_f32_e32 v14, v35, v35
	s_nop 1
	v_add_f32_dpp v14, v14, v14 row_ror:8 row_mask:0xf bank_mask:0xf bound_ctrl:1
	s_nop 1
	v_add_f32_dpp v14, v14, v14 row_ror:4 row_mask:0xf bank_mask:0xf bound_ctrl:1
	s_nop 1
	v_add_f32_dpp v14, v14, v14 row_ror:2 row_mask:0xf bank_mask:0xf bound_ctrl:1
	s_nop 1
	v_add_f32_dpp v14, v14, v14 row_ror:1 row_mask:0xf bank_mask:0xf bound_ctrl:1
	v_mov_b32_e32 v15, v14
	s_nop 1
	v_permlane16_swap_b32_e32 v14, v15
	v_add_f32_e32 v14, v14, v15
	v_mov_b32_e32 v15, v14
	s_nop 1
	v_permlane32_swap_b32_e32 v14, v15
	v_add_f32_e32 v14, v14, v15
	v_fmamk_f32 v14, v14, 0x3b800000, v9
	v_mul_f32_e32 v15, 0x4b800000, v14
	v_cmp_gt_f32_e32 vcc, s0, v14
	s_nop 1
	v_cndmask_b32_e32 v14, v14, v15, vcc
	v_rsq_f32_e32 v14, v14
	s_nop 0
	v_mul_f32_e32 v15, 0x45800000, v14
	v_cndmask_b32_e32 v14, v14, v15, vcc
	v_mul_f32_e32 v32, v32, v14
	v_mul_f32_e32 v33, v33, v14
	v_mul_f32_e32 v34, v34, v14
	v_mul_f32_e32 v35, v35, v14
	v_mul_f32_e32 v32, v0, v32
	v_mul_f32_e32 v33, v1, v33
	v_mul_f32_e32 v34, v2, v34
	v_mul_f32_e32 v35, v3, v35
	v_cvt_pk_bf16_f32 v32, v32, v33
	v_cvt_pk_bf16_f32 v33, v34, v35
	s_waitcnt vmcnt(11)
	v_mul_f32_e32 v14, v37, v37
	v_fmac_f32_e32 v14, v36, v36
	v_fmac_f32_e32 v14, v38, v38
	v_fmac_f32_e32 v14, v39, v39
	s_nop 1
	v_add_f32_dpp v14, v14, v14 row_ror:8 row_mask:0xf bank_mask:0xf bound_ctrl:1
	s_nop 1
	v_add_f32_dpp v14, v14, v14 row_ror:4 row_mask:0xf bank_mask:0xf bound_ctrl:1
	s_nop 1
	v_add_f32_dpp v14, v14, v14 row_ror:2 row_mask:0xf bank_mask:0xf bound_ctrl:1
	s_nop 1
	v_add_f32_dpp v14, v14, v14 row_ror:1 row_mask:0xf bank_mask:0xf bound_ctrl:1
	v_mov_b32_e32 v15, v14
	s_nop 1
	v_permlane16_swap_b32_e32 v14, v15
	v_add_f32_e32 v14, v14, v15
	v_mov_b32_e32 v15, v14
	s_nop 1
	v_permlane32_swap_b32_e32 v14, v15
	v_add_f32_e32 v14, v14, v15
	v_fmamk_f32 v14, v14, 0x3b800000, v9
	v_mul_f32_e32 v15, 0x4b800000, v14
	v_cmp_gt_f32_e32 vcc, s0, v14
	s_nop 1
	v_cndmask_b32_e32 v14, v14, v15, vcc
	v_rsq_f32_e32 v14, v14
	s_nop 0
	v_mul_f32_e32 v15, 0x45800000, v14
	v_cndmask_b32_e32 v14, v14, v15, vcc
	v_mul_f32_e32 v36, v36, v14
	v_mul_f32_e32 v37, v37, v14
	v_mul_f32_e32 v38, v38, v14
	v_mul_f32_e32 v39, v39, v14
	v_mul_f32_e32 v36, v0, v36
	v_mul_f32_e32 v37, v1, v37
	v_mul_f32_e32 v38, v2, v38
	v_mul_f32_e32 v39, v3, v39
	v_cvt_pk_bf16_f32 v36, v36, v37
	v_cvt_pk_bf16_f32 v37, v38, v39
	s_waitcnt vmcnt(10)
	v_mul_f32_e32 v14, v41, v41
	v_fmac_f32_e32 v14, v40, v40
	v_fmac_f32_e32 v14, v42, v42
	v_fmac_f32_e32 v14, v43, v43
	s_nop 1
	v_add_f32_dpp v14, v14, v14 row_ror:8 row_mask:0xf bank_mask:0xf bound_ctrl:1
	s_nop 1
	v_add_f32_dpp v14, v14, v14 row_ror:4 row_mask:0xf bank_mask:0xf bound_ctrl:1
	s_nop 1
	v_add_f32_dpp v14, v14, v14 row_ror:2 row_mask:0xf bank_mask:0xf bound_ctrl:1
	s_nop 1
	v_add_f32_dpp v14, v14, v14 row_ror:1 row_mask:0xf bank_mask:0xf bound_ctrl:1
	v_mov_b32_e32 v15, v14
	s_nop 1
	v_permlane16_swap_b32_e32 v14, v15
	v_add_f32_e32 v14, v14, v15
	v_mov_b32_e32 v15, v14
	s_nop 1
	v_permlane32_swap_b32_e32 v14, v15
	v_add_f32_e32 v14, v14, v15
	v_fmamk_f32 v14, v14, 0x3b800000, v9
	v_mul_f32_e32 v15, 0x4b800000, v14
	v_cmp_gt_f32_e32 vcc, s0, v14
	s_nop 1
	v_cndmask_b32_e32 v14, v14, v15, vcc
	v_rsq_f32_e32 v14, v14
	s_nop 0
	v_mul_f32_e32 v15, 0x45800000, v14
	v_cndmask_b32_e32 v14, v14, v15, vcc
	v_mul_f32_e32 v40, v40, v14
	v_mul_f32_e32 v41, v41, v14
	v_mul_f32_e32 v42, v42, v14
	v_mul_f32_e32 v43, v43, v14
	v_mul_f32_e32 v40, v0, v40
	v_mul_f32_e32 v41, v1, v41
	v_mul_f32_e32 v42, v2, v42
	v_mul_f32_e32 v43, v3, v43
	v_cvt_pk_bf16_f32 v40, v40, v41
	v_cvt_pk_bf16_f32 v41, v42, v43
	s_waitcnt vmcnt(9)
	v_mul_f32_e32 v14, v45, v45
	v_fmac_f32_e32 v14, v44, v44
	v_fmac_f32_e32 v14, v46, v46
	v_fmac_f32_e32 v14, v47, v47
	s_nop 1
	v_add_f32_dpp v14, v14, v14 row_ror:8 row_mask:0xf bank_mask:0xf bound_ctrl:1
	s_nop 1
	v_add_f32_dpp v14, v14, v14 row_ror:4 row_mask:0xf bank_mask:0xf bound_ctrl:1
	s_nop 1
	v_add_f32_dpp v14, v14, v14 row_ror:2 row_mask:0xf bank_mask:0xf bound_ctrl:1
	s_nop 1
	v_add_f32_dpp v14, v14, v14 row_ror:1 row_mask:0xf bank_mask:0xf bound_ctrl:1
	v_mov_b32_e32 v15, v14
	s_nop 1
	v_permlane16_swap_b32_e32 v14, v15
	v_add_f32_e32 v14, v14, v15
	v_mov_b32_e32 v15, v14
	s_nop 1
	v_permlane32_swap_b32_e32 v14, v15
	v_add_f32_e32 v14, v14, v15
	v_fmamk_f32 v14, v14, 0x3b800000, v9
	v_mul_f32_e32 v15, 0x4b800000, v14
	v_cmp_gt_f32_e32 vcc, s0, v14
	s_nop 1
	v_cndmask_b32_e32 v14, v14, v15, vcc
	v_rsq_f32_e32 v14, v14
	s_nop 0
	v_mul_f32_e32 v15, 0x45800000, v14
	v_cndmask_b32_e32 v14, v14, v15, vcc
	v_mul_f32_e32 v44, v44, v14
	v_mul_f32_e32 v45, v45, v14
	v_mul_f32_e32 v46, v46, v14
	v_mul_f32_e32 v47, v47, v14
	v_mul_f32_e32 v44, v0, v44
	v_mul_f32_e32 v45, v1, v45
	v_mul_f32_e32 v46, v2, v46
	v_mul_f32_e32 v47, v3, v47
	v_cvt_pk_bf16_f32 v44, v44, v45
	v_cvt_pk_bf16_f32 v45, v46, v47
	s_waitcnt vmcnt(8)
; __device__ __forceinline__ unsigned cvt_pk_bf16(float lo, float hi) { unsigned r; asm("v_cvt_pk_bf16_f32 %0, %1, %2" : "=v"(r) : "v"(lo), "v"(hi)); return r; }
; __device__ __forceinline__ float wave_sum(float s, int) { s += dppf<0x128>(s); s += dppf<0x124>(s); s += dppf<0x122>(s); s += dppf<0x121>(s); return psum32(psum16(s)); }
; __device__ __forceinline__ void p3_ckvnorm(const Params& p, int bid, int nb) {
;   int tid = threadIdx.x; asm volatile("" : "+v"(tid));
;   const int lane = tid & 63, wid = tid >> 6;
;   const float* cr = (const float*)(p.ws + OFF_CKVR); bf16_t* cn = (bf16_t*)(p.ws + OFF_CKVN);
;   const f32x4 g = *(const f32x4*)((const float*)(p.ws + OFF_SMALL) + SM_KVN + lane * 4);
;   for (int row = bid * 8 + wid; row < T; row += nb * 8) {
;     const f32x4 v = *(const f32x4*)(cr + (size_t)row * 256 + lane * 4);
;     float s = v[0] * v[0] + v[1] * v[1] + v[2] * v[2] + v[3] * v[3]; s = wave_sum(s, lane);
;     const float r = rsqrtf(s * (1.f / 256.f) + EPS);
;     u32x2 o; o[0] = cvt_pk_bf16(v[0] * r * g[0], v[1] * r * g[1]); o[1] = cvt_pk_bf16(v[2] * r * g[2], v[3] * r * g[3]);
;     *(u32x2*)(cn + (size_t)row * 256 + lane * 4) = o;
;   }
; }
	v_mul_f32_e32 v14, v49, v49
	v_fmac_f32_e32 v14, v48, v48
	v_fmac_f32_e32 v14, v50, v50
	v_fmac_f32_e32 v14, v51, v51
	s_nop 1
	v_add_f32_dpp v14, v14, v14 row_ror:8 row_mask:0xf bank_mask:0xf bound_ctrl:1
	s_nop 1
	v_add_f32_dpp v14, v14, v14 row_ror:4 row_mask:0xf bank_mask:0xf bound_ctrl:1
	s_nop 1
	v_add_f32_dpp v14, v14, v14 row_ror:2 row_mask:0xf bank_mask:0xf bound_ctrl:1
	s_nop 1
	v_add_f32_dpp v14, v14, v14 row_ror:1 row_mask:0xf bank_mask:0xf bound_ctrl:1
	v_mov_b32_e32 v15, v14
	s_nop 1
	v_permlane16_swap_b32_e32 v14, v15
	v_add_f32_e32 v14, v14, v15
	v_mov_b32_e32 v15, v14
	s_nop 1
	v_permlane32_swap_b32_e32 v14, v15
	v_add_f32_e32 v14, v14, v15
	v_fmamk_f32 v14, v14, 0x3b800000, v9
	v_mul_f32_e32 v15, 0x4b800000, v14
	v_cmp_gt_f32_e32 vcc, s0, v14
	s_nop 1
	v_cndmask_b32_e32 v14, v14, v15, vcc
	v_rsq_f32_e32 v14, v14
	s_nop 0
	v_mul_f32_e32 v15, 0x45800000, v14
	v_cndmask_b32_e32 v14, v14, v15, vcc
	v_mul_f32_e32 v48, v48, v14
	v_mul_f32_e32 v49, v49, v14
	v_mul_f32_e32 v50, v50, v14
	v_mul_f32_e32 v51, v51, v14
	v_mul_f32_e32 v48, v0, v48
	v_mul_f32_e32 v49, v1, v49
	v_mul_f32_e32 v50, v2, v50
	v_mul_f32_e32 v51, v3, v51
	v_cvt_pk_bf16_f32 v48, v48, v49
	v_cvt_pk_bf16_f32 v49, v50, v51
	s_waitcnt vmcnt(7)
	v_mul_f32_e32 v14, v53, v53
	v_fmac_f32_e32 v14, v52, v52
	v_fmac_f32_e32 v14, v54, v54
	v_fmac_f32_e32 v14, v55, v55
	s_nop 1
	v_add_f32_dpp v14, v14, v14 row_ror:8 row_mask:0xf bank_mask:0xf bound_ctrl:1
	s_nop 1
	v_add_f32_dpp v14, v14, v14 row_ror:4 row_mask:0xf bank_mask:0xf bound_ctrl:1
	s_nop 1
	v_add_f32_dpp v14, v14, v14 row_ror:2 row_mask:0xf bank_mask:0xf bound_ctrl:1
	s_nop 1
	v_add_f32_dpp v14, v14, v14 row_ror:1 row_mask:0xf bank_mask:0xf bound_ctrl:1
	v_mov_b32_e32 v15, v14
	s_nop 1
	v_permlane16_swap_b32_e32 v14, v15
	v_add_f32_e32 v14, v14, v15
	v_mov_b32_e32 v15, v14
	s_nop 1
	v_permlane32_swap_b32_e32 v14, v15
	v_add_f32_e32 v14, v14, v15
	v_fmamk_f32 v14, v14, 0x3b800000, v9
	v_mul_f32_e32 v15, 0x4b800000, v14
	v_cmp_gt_f32_e32 vcc, s0, v14
	s_nop 1
	v_cndmask_b32_e32 v14, v14, v15, vcc
	v_rsq_f32_e32 v14, v14
	s_nop 0
	v_mul_f32_e32 v15, 0x45800000, v14
	v_cndmask_b32_e32 v14, v14, v15, vcc
	v_mul_f32_e32 v52, v52, v14
	v_mul_f32_e32 v53, v53, v14
	v_mul_f32_e32 v54, v54, v14
	v_mul_f32_e32 v55, v55, v14
	v_mul_f32_e32 v52, v0, v52
	v_mul_f32_e32 v53, v1, v53
	v_mul_f32_e32 v54, v2, v54
	v_mul_f32_e32 v55, v3, v55
	v_cvt_pk_bf16_f32 v52, v52, v53
	v_cvt_pk_bf16_f32 v53, v54, v55
	s_waitcnt vmcnt(6)
	v_mul_f32_e32 v14, v57, v57
	v_fmac_f32_e32 v14, v56, v56
	v_fmac_f32_e32 v14, v58, v58
	v_fmac_f32_e32 v14, v59, v59
	s_nop 1
	v_add_f32_dpp v14, v14, v14 row_ror:8 row_mask:0xf bank_mask:0xf bound_ctrl:1
	s_nop 1
	v_add_f32_dpp v14, v14, v14 row_ror:4 row_mask:0xf bank_mask:0xf bound_ctrl:1
	s_nop 1
	v_add_f32_dpp v14, v14, v14 row_ror:2 row_mask:0xf bank_mask:0xf bound_ctrl:1
	s_nop 1
	v_add_f32_dpp v14, v14, v14 row_ror:1 row_mask:0xf bank_mask:0xf bound_ctrl:1
	v_mov_b32_e32 v15, v14
	s_nop 1
	v_permlane16_swap_b32_e32 v14, v15
	v_add_f32_e32 v14, v14, v15
	v_mov_b32_e32 v15, v14
	s_nop 1
	v_permlane32_swap_b32_e32 v14, v15
	v_add_f32_e32 v14, v14, v15
	v_fmamk_f32 v14, v14, 0x3b800000, v9
	v_mul_f32_e32 v15, 0x4b800000, v14
	v_cmp_gt_f32_e32 vcc, s0, v14
	s_nop 1
	v_cndmask_b32_e32 v14, v14, v15, vcc
	v_rsq_f32_e32 v14, v14
	s_nop 0
	v_mul_f32_e32 v15, 0x45800000, v14
	v_cndmask_b32_e32 v14, v14, v15, vcc
	v_mul_f32_e32 v56, v56, v14
	v_mul_f32_e32 v57, v57, v14
	v_mul_f32_e32 v58, v58, v14
	v_mul_f32_e32 v59, v59, v14
	v_mul_f32_e32 v56, v0, v56
	v_mul_f32_e32 v57, v1, v57
	v_mul_f32_e32 v58, v2, v58
	v_mul_f32_e32 v59, v3, v59
	v_cvt_pk_bf16_f32 v56, v56, v57
	v_cvt_pk_bf16_f32 v57, v58, v59
	s_waitcnt vmcnt(5)
	v_mul_f32_e32 v14, v61, v61
	v_fmac_f32_e32 v14, v60, v60
	v_fmac_f32_e32 v14, v62, v62
	v_fmac_f32_e32 v14, v63, v63
	s_nop 1
	v_add_f32_dpp v14, v14, v14 row_ror:8 row_mask:0xf bank_mask:0xf bound_ctrl:1
	s_nop 1
	v_add_f32_dpp v14, v14, v14 row_ror:4 row_mask:0xf bank_mask:0xf bound_ctrl:1
	s_nop 1
	v_add_f32_dpp v14, v14, v14 row_ror:2 row_mask:0xf bank_mask:0xf bound_ctrl:1
	s_nop 1
	v_add_f32_dpp v14, v14, v14 row_ror:1 row_mask:0xf bank_mask:0xf bound_ctrl:1
	v_mov_b32_e32 v15, v14
	s_nop 1
	v_permlane16_swap_b32_e32 v14, v15
	v_add_f32_e32 v14, v14, v15
	v_mov_b32_e32 v15, v14
	s_nop 1
	v_permlane32_swap_b32_e32 v14, v15
	v_add_f32_e32 v14, v14, v15
	v_fmamk_f32 v14, v14, 0x3b800000, v9
	v_mul_f32_e32 v15, 0x4b800000, v14
	v_cmp_gt_f32_e32 vcc, s0, v14
	s_nop 1
	v_cndmask_b32_e32 v14, v14, v15, vcc
	v_rsq_f32_e32 v14, v14
	s_nop 0
	v_mul_f32_e32 v15, 0x45800000, v14
	v_cndmask_b32_e32 v14, v14, v15, vcc
	v_mul_f32_e32 v60, v60, v14
	v_mul_f32_e32 v61, v61, v14
	v_mul_f32_e32 v62, v62, v14
	v_mul_f32_e32 v63, v63, v14
	v_mul_f32_e32 v60, v0, v60
	v_mul_f32_e32 v61, v1, v61
	v_mul_f32_e32 v62, v2, v62
	v_mul_f32_e32 v63, v3, v63
	v_cvt_pk_bf16_f32 v60, v60, v61
	v_cvt_pk_bf16_f32 v61, v62, v63
	s_waitcnt vmcnt(4)
	v_mul_f32_e32 v14, v65, v65
	v_fmac_f32_e32 v14, v64, v64
	v_fmac_f32_e32 v14, v66, v66
	v_fmac_f32_e32 v14, v67, v67
	s_nop 1
	v_add_f32_dpp v14, v14, v14 row_ror:8 row_mask:0xf bank_mask:0xf bound_ctrl:1
	s_nop 1
	v_add_f32_dpp v14, v14, v14 row_ror:4 row_mask:0xf bank_mask:0xf bound_ctrl:1
	s_nop 1
	v_add_f32_dpp v14, v14, v14 row_ror:2 row_mask:0xf bank_mask:0xf bound_ctrl:1
	s_nop 1
	v_add_f32_dpp v14, v14, v14 row_ror:1 row_mask:0xf bank_mask:0xf bound_ctrl:1
	v_mov_b32_e32 v15, v14
	s_nop 1
	v_permlane16_swap_b32_e32 v14, v15
	v_add_f32_e32 v14, v14, v15
	v_mov_b32_e32 v15, v14
	s_nop 1
	v_permlane32_swap_b32_e32 v14, v15
	v_add_f32_e32 v14, v14, v15
	v_fmamk_f32 v14, v14, 0x3b800000, v9
	v_mul_f32_e32 v15, 0x4b800000, v14
	v_cmp_gt_f32_e32 vcc, s0, v14
	s_nop 1
	v_cndmask_b32_e32 v14, v14, v15, vcc
	v_rsq_f32_e32 v14, v14
	s_nop 0
	v_mul_f32_e32 v15, 0x45800000, v14
	v_cndmask_b32_e32 v14, v14, v15, vcc
	v_mul_f32_e32 v64, v64, v14
	v_mul_f32_e32 v65, v65, v14
	v_mul_f32_e32 v66, v66, v14
	v_mul_f32_e32 v67, v67, v14
	v_mul_f32_e32 v64, v0, v64
	v_mul_f32_e32 v65, v1, v65
	v_mul_f32_e32 v66, v2, v66
	v_mul_f32_e32 v67, v3, v67
	v_cvt_pk_bf16_f32 v64, v64, v65
	v_cvt_pk_bf16_f32 v65, v66, v67
	s_waitcnt vmcnt(3)
; __device__ __forceinline__ unsigned cvt_pk_bf16(float lo, float hi) { unsigned r; asm("v_cvt_pk_bf16_f32 %0, %1, %2" : "=v"(r) : "v"(lo), "v"(hi)); return r; }
; __device__ __forceinline__ float wave_sum(float s, int) { s += dppf<0x128>(s); s += dppf<0x124>(s); s += dppf<0x122>(s); s += dppf<0x121>(s); return psum32(psum16(s)); }
; __device__ __forceinline__ void p3_ckvnorm(const Params& p, int bid, int nb) {
;     ...
;   for (int row = bid * 8 + wid; row < T; row += nb * 8) {
;     const f32x4 v = *(const f32x4*)(cr + (size_t)row * 256 + lane * 4);
;     float s = v[0] * v[0] + v[1] * v[1] + v[2] * v[2] + v[3] * v[3]; s = wave_sum(s, lane);
;     const float r = rsqrtf(s * (1.f / 256.f) + EPS);
;     u32x2 o; o[0] = cvt_pk_bf16(v[0] * r * g[0], v[1] * r * g[1]); o[1] = cvt_pk_bf16(v[2] * r * g[2], v[3] * r * g[3]);
;     *(u32x2*)(cn + (size_t)row * 256 + lane * 4) = o;
;   }
	v_mul_f32_e32 v14, v69, v69
	v_fmac_f32_e32 v14, v68, v68
	v_fmac_f32_e32 v14, v70, v70
	v_fmac_f32_e32 v14, v71, v71
	s_nop 1
	v_add_f32_dpp v14, v14, v14 row_ror:8 row_mask:0xf bank_mask:0xf bound_ctrl:1
	s_nop 1
	v_add_f32_dpp v14, v14, v14 row_ror:4 row_mask:0xf bank_mask:0xf bound_ctrl:1
	s_nop 1
	v_add_f32_dpp v14, v14, v14 row_ror:2 row_mask:0xf bank_mask:0xf bound_ctrl:1
	s_nop 1
	v_add_f32_dpp v14, v14, v14 row_ror:1 row_mask:0xf bank_mask:0xf bound_ctrl:1
	v_mov_b32_e32 v15, v14
	s_nop 1
	v_permlane16_swap_b32_e32 v14, v15
	v_add_f32_e32 v14, v14, v15
	v_mov_b32_e32 v15, v14
	s_nop 1
	v_permlane32_swap_b32_e32 v14, v15
	v_add_f32_e32 v14, v14, v15
	v_fmamk_f32 v14, v14, 0x3b800000, v9
	v_mul_f32_e32 v15, 0x4b800000, v14
	v_cmp_gt_f32_e32 vcc, s0, v14
	s_nop 1
	v_cndmask_b32_e32 v14, v14, v15, vcc
	v_rsq_f32_e32 v14, v14
	s_nop 0
	v_mul_f32_e32 v15, 0x45800000, v14
	v_cndmask_b32_e32 v14, v14, v15, vcc
	v_mul_f32_e32 v68, v68, v14
	v_mul_f32_e32 v69, v69, v14
	v_mul_f32_e32 v70, v70, v14
	v_mul_f32_e32 v71, v71, v14
	v_mul_f32_e32 v68, v0, v68
	v_mul_f32_e32 v69, v1, v69
	v_mul_f32_e32 v70, v2, v70
	v_mul_f32_e32 v71, v3, v71
	v_cvt_pk_bf16_f32 v68, v68, v69
	v_cvt_pk_bf16_f32 v69, v70, v71
	s_waitcnt vmcnt(2)
	v_mul_f32_e32 v14, v73, v73
	v_fmac_f32_e32 v14, v72, v72
	v_fmac_f32_e32 v14, v74, v74
	v_fmac_f32_e32 v14, v75, v75
	s_nop 1
	v_add_f32_dpp v14, v14, v14 row_ror:8 row_mask:0xf bank_mask:0xf bound_ctrl:1
	s_nop 1
	v_add_f32_dpp v14, v14, v14 row_ror:4 row_mask:0xf bank_mask:0xf bound_ctrl:1
	s_nop 1
	v_add_f32_dpp v14, v14, v14 row_ror:2 row_mask:0xf bank_mask:0xf bound_ctrl:1
	s_nop 1
	v_add_f32_dpp v14, v14, v14 row_ror:1 row_mask:0xf bank_mask:0xf bound_ctrl:1
	v_mov_b32_e32 v15, v14
	s_nop 1
	v_permlane16_swap_b32_e32 v14, v15
	v_add_f32_e32 v14, v14, v15
	v_mov_b32_e32 v15, v14
	s_nop 1
	v_permlane32_swap_b32_e32 v14, v15
	v_add_f32_e32 v14, v14, v15
	v_fmamk_f32 v14, v14, 0x3b800000, v9
	v_mul_f32_e32 v15, 0x4b800000, v14
	v_cmp_gt_f32_e32 vcc, s0, v14
	s_nop 1
	v_cndmask_b32_e32 v14, v14, v15, vcc
	v_rsq_f32_e32 v14, v14
	s_nop 0
	v_mul_f32_e32 v15, 0x45800000, v14
	v_cndmask_b32_e32 v14, v14, v15, vcc
	v_mul_f32_e32 v72, v72, v14
	v_mul_f32_e32 v73, v73, v14
	v_mul_f32_e32 v74, v74, v14
	v_mul_f32_e32 v75, v75, v14
	v_mul_f32_e32 v72, v0, v72
	v_mul_f32_e32 v73, v1, v73
	v_mul_f32_e32 v74, v2, v74
	v_mul_f32_e32 v75, v3, v75
	v_cvt_pk_bf16_f32 v72, v72, v73
	v_cvt_pk_bf16_f32 v73, v74, v75
	s_waitcnt vmcnt(1)
	v_mul_f32_e32 v14, v77, v77
	v_fmac_f32_e32 v14, v76, v76
	v_fmac_f32_e32 v14, v78, v78
	v_fmac_f32_e32 v14, v79, v79
	s_nop 1
	v_add_f32_dpp v14, v14, v14 row_ror:8 row_mask:0xf bank_mask:0xf bound_ctrl:1
	s_nop 1
	v_add_f32_dpp v14, v14, v14 row_ror:4 row_mask:0xf bank_mask:0xf bound_ctrl:1
	s_nop 1
	v_add_f32_dpp v14, v14, v14 row_ror:2 row_mask:0xf bank_mask:0xf bound_ctrl:1
	s_nop 1
	v_add_f32_dpp v14, v14, v14 row_ror:1 row_mask:0xf bank_mask:0xf bound_ctrl:1
	v_mov_b32_e32 v15, v14
	s_nop 1
	v_permlane16_swap_b32_e32 v14, v15
	v_add_f32_e32 v14, v14, v15
	v_mov_b32_e32 v15, v14
	s_nop 1
	v_permlane32_swap_b32_e32 v14, v15
	v_add_f32_e32 v14, v14, v15
	v_fmamk_f32 v14, v14, 0x3b800000, v9
	v_mul_f32_e32 v15, 0x4b800000, v14
	v_cmp_gt_f32_e32 vcc, s0, v14
	s_nop 1
	v_cndmask_b32_e32 v14, v14, v15, vcc
	v_rsq_f32_e32 v14, v14
	s_nop 0
	v_mul_f32_e32 v15, 0x45800000, v14
	v_cndmask_b32_e32 v14, v14, v15, vcc
	v_mul_f32_e32 v76, v76, v14
	v_mul_f32_e32 v77, v77, v14
	v_mul_f32_e32 v78, v78, v14
	v_mul_f32_e32 v79, v79, v14
	v_mul_f32_e32 v76, v0, v76
	v_mul_f32_e32 v77, v1, v77
	v_mul_f32_e32 v78, v2, v78
	v_mul_f32_e32 v79, v3, v79
	v_cvt_pk_bf16_f32 v76, v76, v77
	v_cvt_pk_bf16_f32 v77, v78, v79
	s_waitcnt vmcnt(0)
	v_mul_f32_e32 v14, v81, v81
	v_fmac_f32_e32 v14, v80, v80
	v_fmac_f32_e32 v14, v82, v82
	v_fmac_f32_e32 v14, v83, v83
	s_nop 1
	v_add_f32_dpp v14, v14, v14 row_ror:8 row_mask:0xf bank_mask:0xf bound_ctrl:1
	s_nop 1
	v_add_f32_dpp v14, v14, v14 row_ror:4 row_mask:0xf bank_mask:0xf bound_ctrl:1
	s_nop 1
	v_add_f32_dpp v14, v14, v14 row_ror:2 row_mask:0xf bank_mask:0xf bound_ctrl:1
	s_nop 1
	v_add_f32_dpp v14, v14, v14 row_ror:1 row_mask:0xf bank_mask:0xf bound_ctrl:1
	v_mov_b32_e32 v15, v14
	s_nop 1
	v_permlane16_swap_b32_e32 v14, v15
	v_add_f32_e32 v14, v14, v15
	v_mov_b32_e32 v15, v14
	s_nop 1
	v_permlane32_swap_b32_e32 v14, v15
	v_add_f32_e32 v14, v14, v15
	v_fmamk_f32 v14, v14, 0x3b800000, v9
	v_mul_f32_e32 v15, 0x4b800000, v14
	v_cmp_gt_f32_e32 vcc, s0, v14
	s_nop 1
	v_cndmask_b32_e32 v14, v14, v15, vcc
	v_rsq_f32_e32 v14, v14
	s_nop 0
	v_mul_f32_e32 v15, 0x45800000, v14
	v_cndmask_b32_e32 v14, v14, v15, vcc
	v_mul_f32_e32 v80, v80, v14
	v_mul_f32_e32 v81, v81, v14
	v_mul_f32_e32 v82, v82, v14
	v_mul_f32_e32 v83, v83, v14
	v_mul_f32_e32 v80, v0, v80
	v_mul_f32_e32 v81, v1, v81
	v_mul_f32_e32 v82, v2, v82
	v_mul_f32_e32 v83, v3, v83
	v_cvt_pk_bf16_f32 v80, v80, v81
	v_cvt_pk_bf16_f32 v81, v82, v83
	global_store_dwordx2 v[6:7], v[20:21], off
	v_lshl_add_u64 v[6:7], v[6:7], 0, s[10:11]
	global_store_dwordx2 v[6:7], v[24:25], off
	v_lshl_add_u64 v[6:7], v[6:7], 0, s[10:11]
	global_store_dwordx2 v[6:7], v[28:29], off
	v_lshl_add_u64 v[6:7], v[6:7], 0, s[10:11]
	global_store_dwordx2 v[6:7], v[32:33], off
	v_lshl_add_u64 v[6:7], v[6:7], 0, s[10:11]
	global_store_dwordx2 v[6:7], v[36:37], off
	v_lshl_add_u64 v[6:7], v[6:7], 0, s[10:11]
	global_store_dwordx2 v[6:7], v[40:41], off
	v_lshl_add_u64 v[6:7], v[6:7], 0, s[10:11]
	global_store_dwordx2 v[6:7], v[44:45], off
	v_lshl_add_u64 v[6:7], v[6:7], 0, s[10:11]
	global_store_dwordx2 v[6:7], v[48:49], off
	v_lshl_add_u64 v[6:7], v[6:7], 0, s[10:11]
	global_store_dwordx2 v[6:7], v[52:53], off
	v_lshl_add_u64 v[6:7], v[6:7], 0, s[10:11]
	global_store_dwordx2 v[6:7], v[56:57], off
	v_lshl_add_u64 v[6:7], v[6:7], 0, s[10:11]
	global_store_dwordx2 v[6:7], v[60:61], off
	v_lshl_add_u64 v[6:7], v[6:7], 0, s[10:11]
	global_store_dwordx2 v[6:7], v[64:65], off
	v_lshl_add_u64 v[6:7], v[6:7], 0, s[10:11]
	global_store_dwordx2 v[6:7], v[68:69], off
	v_lshl_add_u64 v[6:7], v[6:7], 0, s[10:11]
	global_store_dwordx2 v[6:7], v[72:73], off
	v_lshl_add_u64 v[6:7], v[6:7], 0, s[10:11]
	global_store_dwordx2 v[6:7], v[76:77], off
	v_lshl_add_u64 v[6:7], v[6:7], 0, s[10:11]
	global_store_dwordx2 v[6:7], v[80:81], off
	s_branch .LBB0_945

; __device__ __forceinline__ float silu_fast(float z) { return z * __builtin_amdgcn_rcpf(1.f + __builtin_amdgcn_exp2f(-1.4426950408889634f * z)); }
;   __device__ __forceinline__ void operator()(const Acc& acc, const GUnit& u, int wr, int wc, int fr, int fq) const {
;     const int row0 = u.pm * 256 + wr * 64 + fr; const int col0 = u.pn * 256 + wc * 32 + 8 * fq;
; #pragma unroll
;     for (int ai = 0; ai < 2; ++ai)
; #pragma unroll
;       for (int m = 0; m < 4; ++m) {
;         const size_t off = (size_t)(row0 + ai * 128 + m * 16) * 4096 + col0;
; #pragma unroll
;         for (int bj = 0; bj < 2; ++bj) {
;           const u32x2 zw = *(const u32x2*)(Z + off + bj * 128);
;           typedef float f32x2v __attribute__((ext_vector_type(2)));
;           const f32x2v z0 = __builtin_amdgcn_cvt_pk_f32_fp8(zw[0], false), z1 = __builtin_amdgcn_cvt_pk_f32_fp8(zw[0], true), z2 = __builtin_amdgcn_cvt_pk_f32_fp8(zw[1], false), z3 = __builtin_amdgcn_cvt_pk_f32_fp8(zw[1], true);
;           f32x4 a = acc[ai][bj][m][0] * osc, b = acc[ai][bj][m][1] * osc;
;           a[0] *= silu_fast(z0[0]); a[1] *= silu_fast(z0[1]); a[2] *= silu_fast(z1[0]); a[3] *= silu_fast(z1[1]);
;           b[0] *= silu_fast(z2[0]); b[1] *= silu_fast(z2[1]); b[2] *= silu_fast(z3[0]); b[3] *= silu_fast(z3[1]);
;           u32x2 w; w[0] = __builtin_amdgcn_cvt_pk_fp8_f32(a[0], a[1], 0, false); w[0] = __builtin_amdgcn_cvt_pk_fp8_f32(a[2], a[3], w[0], true);
;           w[1] = __builtin_amdgcn_cvt_pk_fp8_f32(b[0], b[1], 0, false); w[1] = __builtin_amdgcn_cvt_pk_fp8_f32(b[2], b[3], w[1], true);
;           *(u32x2*)(Y + off + bj * 128) = w;
.LBB0_1047:
	v_mov_b32_e32 v132, v200
	s_lshl_b32 s28, s28, 8
	v_readfirstlane_b32 s23, v132
	s_ashr_i32 s30, s23, 2
	s_andn2_b32 s30, s30, 63
	s_lshr_b32 s23, s23, 1
	s_add_i32 s30, s30, s28
	s_lshl_b32 s28, s46, 8
	s_and_b32 s23, s23, 0x60
	v_and_or_b32 v134, v132, 15, s30
	s_or_b32 s23, s23, s28
	v_lshrrev_b32_e32 v132, 1, v132
	v_and_or_b32 v136, v132, 24, s23
	v_ashrrev_i32_e32 v135, 31, v134
	v_ashrrev_i32_e32 v137, 31, v136
	v_lshlrev_b64 v[132:133], 12, v[134:135]
	v_readlane_b32 s30, v254, 38
	v_lshl_add_u64 v[132:133], v[132:133], 0, v[136:137]
	v_readlane_b32 s31, v254, 39
	v_pk_mul_f32 v[104:105], v[104:105], s[12:13] op_sel_hi:[1,0]
	v_mov_b32_e32 v147, 0
	v_lshl_add_u64 v[142:143], s[30:31], 0, v[132:133]
	global_load_dwordx2 v[214:215], v[142:143], off
	global_load_dwordx2 v[216:217], v[142:143], off offset:128
	s_mov_b64 s[60:61], 0x10000
	v_lshl_add_u64 v[246:247], v[142:143], 0, s[60:61]
	global_load_dwordx2 v[218:219], v[246:247], off
	global_load_dwordx2 v[220:221], v[246:247], off offset:128
	s_mov_b64 s[60:61], 0x20000
	v_lshl_add_u64 v[248:249], v[142:143], 0, s[60:61]
	global_load_dwordx2 v[222:223], v[248:249], off
	global_load_dwordx2 v[224:225], v[248:249], off offset:128
	s_mov_b64 s[60:61], 0x30000
	v_lshl_add_u64 v[246:247], v[142:143], 0, s[60:61]
	global_load_dwordx2 v[226:227], v[246:247], off
	global_load_dwordx2 v[228:229], v[246:247], off offset:128
	s_mov_b64 s[60:61], 0x80000
	v_lshl_add_u64 v[248:249], v[142:143], 0, s[60:61]
	global_load_dwordx2 v[230:231], v[248:249], off
	global_load_dwordx2 v[232:233], v[248:249], off offset:128
	s_mov_b64 s[60:61], 0x90000
	v_lshl_add_u64 v[246:247], v[142:143], 0, s[60:61]
	global_load_dwordx2 v[234:235], v[246:247], off
	global_load_dwordx2 v[236:237], v[246:247], off offset:128
	s_mov_b64 s[60:61], 0xa0000
	v_lshl_add_u64 v[248:249], v[142:143], 0, s[60:61]
	global_load_dwordx2 v[238:239], v[248:249], off
	global_load_dwordx2 v[240:241], v[248:249], off offset:128
	s_mov_b64 s[60:61], 0xb0000
	v_lshl_add_u64 v[246:247], v[142:143], 0, s[60:61]
	global_load_dwordx2 v[242:243], v[246:247], off
	global_load_dwordx2 v[244:245], v[246:247], off offset:128
	s_nop 0
	v_pk_mul_f32 v[106:107], v[106:107], s[12:13] op_sel_hi:[1,0]
	v_pk_mul_f32 v[108:109], v[108:109], s[12:13] op_sel_hi:[1,0]
	v_mov_b32_e32 v146, 0
	v_pk_mul_f32 v[110:111], v[110:111], s[12:13] op_sel_hi:[1,0]
	v_pk_mul_f32 v[126:127], v[126:127], s[12:13] op_sel_hi:[1,0]
	v_pk_mul_f32 v[120:121], v[120:121], s[12:13] op_sel_hi:[1,0]
	v_pk_mul_f32 v[122:123], v[122:123], s[12:13] op_sel_hi:[1,0]
	v_pk_mul_f32 v[124:125], v[124:125], s[12:13] op_sel_hi:[1,0]
	v_readlane_b32 s36, v254, 16
	v_readlane_b32 s38, v254, 18
	v_readlane_b32 s39, v254, 19
	v_pk_mul_f32 v[88:89], v[88:89], s[12:13] op_sel_hi:[1,0]
	v_pk_mul_f32 v[90:91], v[90:91], s[12:13] op_sel_hi:[1,0]
	v_pk_mul_f32 v[92:93], v[92:93], s[12:13] op_sel_hi:[1,0]
	v_pk_mul_f32 v[94:95], v[94:95], s[12:13] op_sel_hi:[1,0]
	v_pk_mul_f32 v[112:113], v[112:113], s[12:13] op_sel_hi:[1,0]
	v_pk_mul_f32 v[114:115], v[114:115], s[12:13] op_sel_hi:[1,0]
	v_pk_mul_f32 v[76:77], v[76:77], s[12:13] op_sel_hi:[1,0]
	v_pk_mul_f32 v[78:79], v[78:79], s[12:13] op_sel_hi:[1,0]
	v_pk_mul_f32 v[72:73], v[72:73], s[12:13] op_sel_hi:[1,0]
	v_pk_mul_f32 v[74:75], v[74:75], s[12:13] op_sel_hi:[1,0]
	v_pk_mul_f32 v[96:97], v[96:97], s[12:13] op_sel_hi:[1,0]
	v_pk_mul_f32 v[98:99], v[98:99], s[12:13] op_sel_hi:[1,0]
	v_pk_mul_f32 v[60:61], v[60:61], s[12:13] op_sel_hi:[1,0]
	v_pk_mul_f32 v[62:63], v[62:63], s[12:13] op_sel_hi:[1,0]
	v_pk_mul_f32 v[56:57], v[56:57], s[12:13] op_sel_hi:[1,0]
	v_pk_mul_f32 v[58:59], v[58:59], s[12:13] op_sel_hi:[1,0]
	v_pk_mul_f32 v[80:81], v[80:81], s[12:13] op_sel_hi:[1,0]
	v_pk_mul_f32 v[82:83], v[82:83], s[12:13] op_sel_hi:[1,0]
	v_pk_mul_f32 v[44:45], v[44:45], s[12:13] op_sel_hi:[1,0]
	v_pk_mul_f32 v[46:47], v[46:47], s[12:13] op_sel_hi:[1,0]
	v_pk_mul_f32 v[40:41], v[40:41], s[12:13] op_sel_hi:[1,0]
	v_pk_mul_f32 v[42:43], v[42:43], s[12:13] op_sel_hi:[1,0]
	v_pk_mul_f32 v[64:65], v[64:65], s[12:13] op_sel_hi:[1,0]
	v_pk_mul_f32 v[66:67], v[66:67], s[12:13] op_sel_hi:[1,0]
	v_pk_mul_f32 v[28:29], v[28:29], s[12:13] op_sel_hi:[1,0]
	v_pk_mul_f32 v[30:31], v[30:31], s[12:13] op_sel_hi:[1,0]
	v_pk_mul_f32 v[24:25], v[24:25], s[12:13] op_sel_hi:[1,0]
	v_pk_mul_f32 v[26:27], v[26:27], s[12:13] op_sel_hi:[1,0]
	v_pk_mul_f32 v[48:49], v[48:49], s[12:13] op_sel_hi:[1,0]
	v_pk_mul_f32 v[50:51], v[50:51], s[12:13] op_sel_hi:[1,0]
	v_pk_mul_f32 v[12:13], v[12:13], s[12:13] op_sel_hi:[1,0]
	v_pk_mul_f32 v[14:15], v[14:15], s[12:13] op_sel_hi:[1,0]
	v_pk_mul_f32 v[8:9], v[8:9], s[12:13] op_sel_hi:[1,0]
	v_pk_mul_f32 v[10:11], v[10:11], s[12:13] op_sel_hi:[1,0]
	v_pk_mul_f32 v[32:33], v[32:33], s[12:13] op_sel_hi:[1,0]
	v_pk_mul_f32 v[34:35], v[34:35], s[12:13] op_sel_hi:[1,0]
	v_pk_mul_f32 v[4:5], v[4:5], s[12:13] op_sel_hi:[1,0]
	v_pk_mul_f32 v[6:7], v[6:7], s[12:13] op_sel_hi:[1,0]
	v_pk_mul_f32 v[0:1], v[0:1], s[12:13] op_sel_hi:[1,0]
	v_pk_mul_f32 v[2:3], v[2:3], s[12:13] op_sel_hi:[1,0]
	v_pk_mul_f32 v[16:17], v[16:17], s[12:13] op_sel_hi:[1,0]
	v_pk_mul_f32 v[18:19], v[18:19], s[12:13] op_sel_hi:[1,0]
	s_andn2_b64 vcc, exec, s[20:21]
	s_mov_b64 s[20:21], -1
	v_readlane_b32 s37, v254, 17
	s_waitcnt vmcnt(14)
; __device__ __forceinline__ float silu_fast(float z) { return z * __builtin_amdgcn_rcpf(1.f + __builtin_amdgcn_exp2f(-1.4426950408889634f * z)); }
;   __device__ __forceinline__ void operator()(const Acc& acc, const GUnit& u, int wr, int wc, int fr, int fq) const {
;     ...
;           const u32x2 zw = *(const u32x2*)(Z + off + bj * 128);
;           typedef float f32x2v __attribute__((ext_vector_type(2)));
;           const f32x2v z0 = __builtin_amdgcn_cvt_pk_f32_fp8(zw[0], false), z1 = __builtin_amdgcn_cvt_pk_f32_fp8(zw[0], true), z2 = __builtin_amdgcn_cvt_pk_f32_fp8(zw[1], false), z3 = __builtin_amdgcn_cvt_pk_f32_fp8(zw[1], true);
;           f32x4 a = acc[ai][bj][m][0] * osc, b = acc[ai][bj][m][1] * osc;
;           a[0] *= silu_fast(z0[0]); a[1] *= silu_fast(z0[1]); a[2] *= silu_fast(z1[0]); a[3] *= silu_fast(z1[1]);
;           b[0] *= silu_fast(z2[0]); b[1] *= silu_fast(z2[1]); b[2] *= silu_fast(z3[0]); b[3] *= silu_fast(z3[1]);
;           u32x2 w; w[0] = __builtin_amdgcn_cvt_pk_fp8_f32(a[0], a[1], 0, false); w[0] = __builtin_amdgcn_cvt_pk_fp8_f32(a[2], a[3], w[0], true);
;           w[1] = __builtin_amdgcn_cvt_pk_fp8_f32(b[0], b[1], 0, false); w[1] = __builtin_amdgcn_cvt_pk_fp8_f32(b[2], b[3], w[1], true);
;           *(u32x2*)(Y + off + bj * 128) = w;
	v_cvt_pk_f32_fp8_e32 v[148:149], v214
	v_cvt_pk_f32_fp8_sdwa v[150:151], v214 src0_sel:WORD_1
	v_cvt_pk_f32_fp8_e32 v[152:153], v215
	v_cvt_pk_f32_fp8_sdwa v[144:145], v215 src0_sel:WORD_1
	v_mul_f32_e32 v135, 0xbfb8aa3b, v148
	v_mul_f32_e32 v160, 0xbfb8aa3b, v149
	v_mul_f32_e32 v161, 0xbfb8aa3b, v150
	v_mul_f32_e32 v162, 0xbfb8aa3b, v151
	v_mul_f32_e32 v163, 0xbfb8aa3b, v152
	v_mul_f32_e32 v164, 0xbfb8aa3b, v153
	v_exp_f32_e32 v135, v135
	v_exp_f32_e32 v160, v160
	v_exp_f32_e32 v161, v161
	v_exp_f32_e32 v162, v162
	v_exp_f32_e32 v163, v163
	v_exp_f32_e32 v164, v164
	v_mul_f32_e32 v165, 0xbfb8aa3b, v144
	v_mul_f32_e32 v166, 0xbfb8aa3b, v145
	v_exp_f32_e32 v165, v165
	v_exp_f32_e32 v166, v166
	v_add_f32_e32 v135, 1.0, v135
	v_add_f32_e32 v160, 1.0, v160
	v_add_f32_e32 v161, 1.0, v161
	v_add_f32_e32 v162, 1.0, v162
	v_add_f32_e32 v163, 1.0, v163
	v_add_f32_e32 v164, 1.0, v164
	v_cvt_pk_f32_fp8_sdwa v[156:157], v216 src0_sel:WORD_1
	v_rcp_f32_e32 v135, v135
	v_rcp_f32_e32 v160, v160
	v_rcp_f32_e32 v161, v161
	v_rcp_f32_e32 v162, v162
	v_rcp_f32_e32 v163, v163
	v_rcp_f32_e32 v164, v164
	v_add_f32_e32 v165, 1.0, v165
	v_add_f32_e32 v166, 1.0, v166
	v_mul_f32_e32 v170, 0xbfb8aa3b, v157
	v_rcp_f32_e32 v165, v165
	v_rcp_f32_e32 v166, v166
	v_mul_f32_e32 v135, v148, v135
	v_mul_f32_e32 v148, v149, v160
	v_mul_f32_e32 v149, v150, v161
	v_mul_f32_e32 v150, v151, v162
	v_mul_f32_e32 v151, v152, v163
	v_mul_f32_e32 v152, v153, v164
	v_exp_f32_e32 v170, v170
	v_mul_f32_e32 v104, v104, v151
	v_mul_f32_e32 v105, v105, v152
	v_cvt_pk_f32_fp8_e32 v[158:159], v217
	v_cvt_pk_fp8_f32 v147, v104, v105
	v_mul_f32_e32 v144, v144, v165
	v_mul_f32_e32 v145, v145, v166
	v_add_f32_e32 v170, 1.0, v170
	v_mul_f32_e32 v106, v106, v144
	v_mul_f32_e32 v107, v107, v145
	v_rcp_f32_e32 v170, v170
	v_mul_f32_e32 v108, v108, v135
	v_mul_f32_e32 v109, v109, v148
	v_cvt_pk_fp8_f32 v147, v106, v107 op_sel:[0,0,1]
	v_mul_f32_e32 v107, 0xbfb8aa3b, v158
	v_cvt_pk_fp8_f32 v146, v108, v109
	v_exp_f32_e32 v107, v107
	v_mul_f32_e32 v109, 0xbfb8aa3b, v159
	v_cvt_pk_f32_fp8_e32 v[154:155], v216
	v_cvt_pk_f32_fp8_sdwa v[142:143], v217 src0_sel:WORD_1
	v_exp_f32_e32 v109, v109
	v_mul_f32_e32 v110, v110, v149
	v_mul_f32_e32 v111, v111, v150
	v_mul_f32_e32 v104, v157, v170
	v_cvt_pk_fp8_f32 v146, v110, v111 op_sel:[0,0,1]
	v_mul_f32_e32 v110, v127, v104
	v_add_f32_e32 v104, 1.0, v107
	v_rcp_f32_e32 v104, v104
	v_add_f32_e32 v107, 1.0, v109
	v_mul_f32_e32 v109, 0xbfb8aa3b, v142
	v_mul_f32_e32 v167, 0xbfb8aa3b, v154
	v_mul_f32_e32 v168, 0xbfb8aa3b, v155
	v_rcp_f32_e32 v107, v107
	v_exp_f32_e32 v109, v109
	v_exp_f32_e32 v167, v167
	v_exp_f32_e32 v168, v168
	v_mul_f32_e32 v104, v158, v104
	v_mul_f32_e32 v111, v120, v104
	v_mul_f32_e32 v104, v159, v107
	v_add_f32_e32 v107, 1.0, v109
	v_mul_f32_e32 v169, 0xbfb8aa3b, v156
	v_add_f32_e32 v167, 1.0, v167
	v_add_f32_e32 v168, 1.0, v168
	v_rcp_f32_e32 v107, v107
	v_mul_f32_e32 v109, 0xbfb8aa3b, v143
	v_exp_f32_e32 v169, v169
	v_rcp_f32_e32 v167, v167
	v_rcp_f32_e32 v168, v168
	v_exp_f32_e32 v109, v109
	v_mul_f32_e32 v120, v121, v104
	v_mul_f32_e32 v104, v142, v107
	v_add_f32_e32 v169, 1.0, v169
	v_mul_f32_e32 v153, v154, v167
	v_mul_f32_e32 v154, v155, v168
	v_mul_f32_e32 v107, v122, v104
	v_add_f32_e32 v104, 1.0, v109
	v_rcp_f32_e32 v169, v169
	v_mul_f32_e32 v105, v124, v153
	v_mul_f32_e32 v108, v125, v154
	v_rcp_f32_e32 v109, v104
	v_mov_b32_e32 v104, 0
	v_cvt_pk_fp8_f32 v104, v105, v108
	v_mov_b32_e32 v105, 0
	v_cvt_pk_fp8_f32 v105, v111, v120
	v_mul_f32_e32 v155, v156, v169
	v_mul_f32_e32 v108, v143, v109
	v_mul_f32_e32 v106, v126, v155
	v_mul_f32_e32 v108, v123, v108
	v_cvt_pk_fp8_f32 v104, v106, v110 op_sel:[0,0,1]
	v_cvt_pk_fp8_f32 v105, v107, v108 op_sel:[0,0,1]
	v_lshl_add_u64 v[106:107], s[38:39], 0, v[132:133]
	global_store_dwordx2 v[106:107], v[146:147], off
	global_store_dwordx2 v[106:107], v[104:105], off offset:128
	v_or_b32_e32 v104, 16, v134
	v_ashrrev_i32_e32 v105, 31, v104
	v_lshlrev_b64 v[104:105], 12, v[104:105]
	v_lshl_add_u64 v[104:105], v[104:105], 0, v[136:137]
	v_lshl_add_u64 v[106:107], s[30:31], 0, v[104:105]
	s_nop 0
	v_mov_b32_e32 v111, 0
	v_mov_b32_e32 v110, 0
	s_waitcnt vmcnt(14)
	v_cvt_pk_f32_fp8_e32 v[124:125], v219
	v_cvt_pk_f32_fp8_e32 v[120:121], v218
	v_cvt_pk_f32_fp8_sdwa v[122:123], v218 src0_sel:WORD_1
	v_cvt_pk_f32_fp8_sdwa v[108:109], v219 src0_sel:WORD_1
	v_mul_f32_e32 v143, 0xbfb8aa3b, v124
	v_mul_f32_e32 v144, 0xbfb8aa3b, v125
	v_exp_f32_e32 v143, v143
	v_exp_f32_e32 v144, v144
	v_mul_f32_e32 v145, 0xbfb8aa3b, v108
	v_mul_f32_e32 v146, 0xbfb8aa3b, v109
	v_exp_f32_e32 v145, v145
	v_exp_f32_e32 v146, v146
	v_add_f32_e32 v143, 1.0, v143
	v_add_f32_e32 v144, 1.0, v144
	v_rcp_f32_e32 v143, v143
	v_rcp_f32_e32 v144, v144
	v_add_f32_e32 v145, 1.0, v145
	v_add_f32_e32 v146, 1.0, v146
	v_mul_f32_e32 v126, 0xbfb8aa3b, v120
	v_rcp_f32_e32 v145, v145
	v_rcp_f32_e32 v146, v146
	v_mul_f32_e32 v124, v124, v143
	v_mul_f32_e32 v125, v125, v144
	v_exp_f32_e32 v126, v126
	v_mul_f32_e32 v88, v88, v124
	v_mul_f32_e32 v89, v89, v125
	v_cvt_pk_fp8_f32 v111, v88, v89
	v_mul_f32_e32 v108, v108, v145
	v_mul_f32_e32 v109, v109, v146
	v_add_f32_e32 v126, 1.0, v126
	v_mul_f32_e32 v88, v90, v108
	v_mul_f32_e32 v89, v91, v109
	v_rcp_f32_e32 v126, v126
	v_cvt_pk_fp8_f32 v111, v88, v89 op_sel:[0,0,1]
	v_cvt_pk_f32_fp8_e32 v[88:89], v220
	v_cvt_pk_f32_fp8_sdwa v[90:91], v220 src0_sel:WORD_1
	v_mul_f32_e32 v120, v120, v126
	v_mul_f32_e32 v92, v92, v120
	v_mul_f32_e32 v106, 0xbfb8aa3b, v88
	v_exp_f32_e32 v120, v106
	v_mul_f32_e32 v127, 0xbfb8aa3b, v121
	v_pk_mul_f32 v[108:109], v[116:117], s[12:13] op_sel_hi:[1,0]
	v_exp_f32_e32 v127, v127
; __device__ __forceinline__ float silu_fast(float z) { return z * __builtin_amdgcn_rcpf(1.f + __builtin_amdgcn_exp2f(-1.4426950408889634f * z)); }
;   __device__ __forceinline__ void operator()(const Acc& acc, const GUnit& u, int wr, int wc, int fr, int fq) const {
;     ...
;           const u32x2 zw = *(const u32x2*)(Z + off + bj * 128);
;           typedef float f32x2v __attribute__((ext_vector_type(2)));
;           const f32x2v z0 = __builtin_amdgcn_cvt_pk_f32_fp8(zw[0], false), z1 = __builtin_amdgcn_cvt_pk_f32_fp8(zw[0], true), z2 = __builtin_amdgcn_cvt_pk_f32_fp8(zw[1], false), z3 = __builtin_amdgcn_cvt_pk_f32_fp8(zw[1], true);
;           f32x4 a = acc[ai][bj][m][0] * osc, b = acc[ai][bj][m][1] * osc;
;           a[0] *= silu_fast(z0[0]); a[1] *= silu_fast(z0[1]); a[2] *= silu_fast(z1[0]); a[3] *= silu_fast(z1[1]);
;           b[0] *= silu_fast(z2[0]); b[1] *= silu_fast(z2[1]); b[2] *= silu_fast(z3[0]); b[3] *= silu_fast(z3[1]);
;           u32x2 w; w[0] = __builtin_amdgcn_cvt_pk_fp8_f32(a[0], a[1], 0, false); w[0] = __builtin_amdgcn_cvt_pk_fp8_f32(a[2], a[3], w[0], true);
;           w[1] = __builtin_amdgcn_cvt_pk_fp8_f32(b[0], b[1], 0, false); w[1] = __builtin_amdgcn_cvt_pk_fp8_f32(b[2], b[3], w[1], true);
;           *(u32x2*)(Y + off + bj * 128) = w;
	v_add_f32_e32 v116, 1.0, v120
	v_rcp_f32_e32 v116, v116
	v_mul_f32_e32 v117, 0xbfb8aa3b, v89
	v_exp_f32_e32 v117, v117
	v_mul_f32_e32 v135, 0xbfb8aa3b, v122
	v_mul_f32_e32 v142, 0xbfb8aa3b, v123
	v_exp_f32_e32 v135, v135
	v_exp_f32_e32 v142, v142
	v_add_f32_e32 v127, 1.0, v127
	v_mul_f32_e32 v88, v88, v116
	v_rcp_f32_e32 v127, v127
	v_mul_f32_e32 v108, v108, v88
	v_add_f32_e32 v88, 1.0, v117
	v_mul_f32_e32 v116, 0xbfb8aa3b, v90
	v_rcp_f32_e32 v88, v88
	v_exp_f32_e32 v116, v116
	v_mul_f32_e32 v117, 0xbfb8aa3b, v91
	v_exp_f32_e32 v117, v117
	v_add_f32_e32 v135, 1.0, v135
	v_add_f32_e32 v142, 1.0, v142
	v_rcp_f32_e32 v135, v135
	v_rcp_f32_e32 v142, v142
	v_mul_f32_e32 v121, v121, v127
	v_mul_f32_e32 v93, v93, v121
	v_mul_f32_e32 v88, v89, v88
	v_add_f32_e32 v89, 1.0, v116
	v_cvt_pk_fp8_f32 v110, v92, v93
	v_cvt_pk_f32_fp8_e32 v[92:93], v221
	v_rcp_f32_e32 v89, v89
	v_add_f32_e32 v116, 1.0, v117
	v_rcp_f32_e32 v116, v116
	v_mul_f32_e32 v122, v122, v135
	v_mul_f32_e32 v123, v123, v142
	v_mul_f32_e32 v94, v94, v122
	v_mul_f32_e32 v95, v95, v123
	v_cvt_pk_fp8_f32 v110, v94, v95 op_sel:[0,0,1]
	v_cvt_pk_f32_fp8_sdwa v[94:95], v221 src0_sel:WORD_1
	v_pk_mul_f32 v[106:107], v[118:119], s[12:13] op_sel_hi:[1,0]
	v_mul_f32_e32 v109, v109, v88
	v_mul_f32_e32 v88, v90, v89
	v_mul_f32_e32 v89, 0xbfb8aa3b, v92
	v_mul_f32_e32 v90, v106, v88
	v_mul_f32_e32 v88, v91, v116
	v_exp_f32_e32 v89, v89
	v_mul_f32_e32 v91, 0xbfb8aa3b, v93
	v_exp_f32_e32 v91, v91
	v_mul_f32_e32 v106, v107, v88
	v_add_f32_e32 v88, 1.0, v89
	v_rcp_f32_e32 v88, v88
	v_add_f32_e32 v89, 1.0, v91
	v_mul_f32_e32 v91, 0xbfb8aa3b, v94
	v_rcp_f32_e32 v89, v89
	v_exp_f32_e32 v91, v91
	v_mul_f32_e32 v88, v92, v88
	v_mul_f32_e32 v92, v112, v88
	v_mul_f32_e32 v88, v93, v89
	v_add_f32_e32 v89, 1.0, v91
	v_rcp_f32_e32 v89, v89
	v_mul_f32_e32 v91, 0xbfb8aa3b, v95
	v_exp_f32_e32 v91, v91
	v_mul_f32_e32 v93, v113, v88
	v_mul_f32_e32 v88, v94, v89
	v_mul_f32_e32 v94, v114, v88
	v_add_f32_e32 v88, 1.0, v91
	v_rcp_f32_e32 v91, v88
	v_mov_b32_e32 v88, 0
	v_mov_b32_e32 v89, 0
	v_cvt_pk_fp8_f32 v88, v108, v109
	v_cvt_pk_fp8_f32 v89, v92, v93
	v_mul_f32_e32 v91, v95, v91
	v_mul_f32_e32 v91, v115, v91
	v_cvt_pk_fp8_f32 v88, v90, v106 op_sel:[0,0,1]
	v_cvt_pk_fp8_f32 v89, v94, v91 op_sel:[0,0,1]
	v_lshl_add_u64 v[90:91], s[38:39], 0, v[104:105]
	global_store_dwordx2 v[90:91], v[110:111], off
	global_store_dwordx2 v[90:91], v[88:89], off offset:128
	v_or_b32_e32 v88, 32, v134
	v_ashrrev_i32_e32 v89, 31, v88
	v_lshlrev_b64 v[88:89], 12, v[88:89]
	v_lshl_add_u64 v[88:89], v[88:89], 0, v[136:137]
	v_lshl_add_u64 v[90:91], s[30:31], 0, v[88:89]
	s_nop 0
	s_waitcnt vmcnt(14)
	v_cvt_pk_f32_fp8_e32 v[94:95], v222
	v_cvt_pk_f32_fp8_sdwa v[104:105], v222 src0_sel:WORD_1
	v_cvt_pk_f32_fp8_e32 v[106:107], v223
	v_cvt_pk_f32_fp8_sdwa v[92:93], v223 src0_sel:WORD_1
	v_mul_f32_e32 v109, 0xbfb8aa3b, v95
	v_mul_f32_e32 v108, 0xbfb8aa3b, v94
	v_exp_f32_e32 v109, v109
	v_mul_f32_e32 v110, 0xbfb8aa3b, v104
	v_exp_f32_e32 v108, v108
	v_exp_f32_e32 v110, v110
	v_mul_f32_e32 v111, 0xbfb8aa3b, v105
	v_add_f32_e32 v109, 1.0, v109
	v_exp_f32_e32 v111, v111
	v_add_f32_e32 v108, 1.0, v108
	v_rcp_f32_e32 v109, v109
	v_add_f32_e32 v110, 1.0, v110
	v_rcp_f32_e32 v108, v108
	v_rcp_f32_e32 v110, v110
	v_add_f32_e32 v111, 1.0, v111
	v_mul_f32_e32 v95, v95, v109
	v_rcp_f32_e32 v111, v111
	v_mul_f32_e32 v94, v94, v108
	v_mul_f32_e32 v77, v77, v95
	v_mul_f32_e32 v95, 0xbfb8aa3b, v106
	v_mul_f32_e32 v76, v76, v94
	v_mul_f32_e32 v94, v104, v110
	v_exp_f32_e32 v95, v95
	v_mul_f32_e32 v104, 0xbfb8aa3b, v107
	v_exp_f32_e32 v104, v104
	v_mul_f32_e32 v78, v78, v94
	v_mul_f32_e32 v94, v105, v111
	v_mul_f32_e32 v79, v79, v94
	v_add_f32_e32 v94, 1.0, v95
	v_rcp_f32_e32 v94, v94
	v_add_f32_e32 v95, 1.0, v104
	v_mul_f32_e32 v104, 0xbfb8aa3b, v92
	v_rcp_f32_e32 v95, v95
	v_exp_f32_e32 v104, v104
	v_mul_f32_e32 v94, v106, v94
	v_mul_f32_e32 v94, v72, v94
	v_mul_f32_e32 v72, v107, v95
	v_add_f32_e32 v95, 1.0, v104
	v_rcp_f32_e32 v95, v95
	v_mul_f32_e32 v104, 0xbfb8aa3b, v93
	v_exp_f32_e32 v104, v104
	v_mul_f32_e32 v105, v73, v72
	v_mul_f32_e32 v72, v92, v95
	v_mul_f32_e32 v74, v74, v72
	v_add_f32_e32 v72, 1.0, v104
	v_rcp_f32_e32 v92, v72
	v_mov_b32_e32 v73, 0
	v_cvt_pk_fp8_f32 v73, v94, v105
	v_mov_b32_e32 v72, 0
	v_cvt_pk_fp8_f32 v72, v76, v77
	v_mul_f32_e32 v76, v93, v92
	v_mul_f32_e32 v75, v75, v76
	v_cvt_pk_fp8_f32 v73, v74, v75 op_sel:[0,0,1]
	v_cvt_pk_f32_fp8_e32 v[74:75], v224
	v_pk_mul_f32 v[94:95], v[100:101], s[12:13] op_sel_hi:[1,0]
	v_cvt_pk_f32_fp8_sdwa v[76:77], v224 src0_sel:WORD_1
	v_cvt_pk_fp8_f32 v72, v78, v79 op_sel:[0,0,1]
	v_mul_f32_e32 v92, 0xbfb8aa3b, v74
	v_exp_f32_e32 v104, v92
	v_mul_f32_e32 v101, 0xbfb8aa3b, v75
	v_exp_f32_e32 v101, v101
	v_cvt_pk_f32_fp8_e32 v[78:79], v225
	v_add_f32_e32 v100, 1.0, v104
	v_rcp_f32_e32 v100, v100
	v_pk_mul_f32 v[92:93], v[102:103], s[12:13] op_sel_hi:[1,0]
	v_cvt_pk_f32_fp8_sdwa v[90:91], v225 src0_sel:WORD_1
	v_mul_f32_e32 v74, v74, v100
	v_mul_f32_e32 v94, v94, v74
	v_add_f32_e32 v74, 1.0, v101
	v_mul_f32_e32 v100, 0xbfb8aa3b, v76
	v_rcp_f32_e32 v74, v74
	v_exp_f32_e32 v100, v100
	v_mul_f32_e32 v101, 0xbfb8aa3b, v77
	v_exp_f32_e32 v101, v101
	v_mul_f32_e32 v74, v75, v74
	v_add_f32_e32 v75, 1.0, v100
	v_rcp_f32_e32 v75, v75
	v_add_f32_e32 v100, 1.0, v101
	v_rcp_f32_e32 v100, v100
	v_mul_f32_e32 v95, v95, v74
	v_mul_f32_e32 v74, v76, v75
	v_mul_f32_e32 v75, 0xbfb8aa3b, v78
	v_mul_f32_e32 v76, v92, v74
	v_mul_f32_e32 v74, v77, v100
	v_exp_f32_e32 v75, v75
	v_mul_f32_e32 v77, 0xbfb8aa3b, v79
	v_exp_f32_e32 v77, v77
	v_mul_f32_e32 v92, v93, v74
	v_add_f32_e32 v74, 1.0, v75
	v_rcp_f32_e32 v74, v74
	v_add_f32_e32 v75, 1.0, v77
	v_mul_f32_e32 v77, 0xbfb8aa3b, v90
	v_rcp_f32_e32 v75, v75
	v_exp_f32_e32 v77, v77
	v_mul_f32_e32 v74, v78, v74
	v_mul_f32_e32 v78, v96, v74
	v_mul_f32_e32 v74, v79, v75
	v_add_f32_e32 v75, 1.0, v77
	v_rcp_f32_e32 v75, v75
	v_mul_f32_e32 v77, 0xbfb8aa3b, v91
	v_exp_f32_e32 v77, v77
	v_mul_f32_e32 v79, v97, v74
	v_mul_f32_e32 v74, v90, v75
	v_mul_f32_e32 v90, v98, v74
	v_add_f32_e32 v74, 1.0, v77
	v_rcp_f32_e32 v77, v74
	v_mov_b32_e32 v74, 0
	v_mov_b32_e32 v75, 0
	v_cvt_pk_fp8_f32 v74, v94, v95
	v_cvt_pk_fp8_f32 v75, v78, v79
	v_mul_f32_e32 v77, v91, v77
	v_mul_f32_e32 v77, v99, v77
	v_cvt_pk_fp8_f32 v74, v76, v92 op_sel:[0,0,1]
	v_cvt_pk_fp8_f32 v75, v90, v77 op_sel:[0,0,1]
	v_lshl_add_u64 v[76:77], s[38:39], 0, v[88:89]
	global_store_dwordx2 v[76:77], v[72:73], off
	global_store_dwordx2 v[76:77], v[74:75], off offset:128
	v_or_b32_e32 v72, 48, v134
	v_ashrrev_i32_e32 v73, 31, v72
	v_lshlrev_b64 v[72:73], 12, v[72:73]
	v_lshl_add_u64 v[72:73], v[72:73], 0, v[136:137]
	v_lshl_add_u64 v[74:75], s[30:31], 0, v[72:73]
	s_nop 0
	s_waitcnt vmcnt(14)
; __device__ __forceinline__ float silu_fast(float z) { return z * __builtin_amdgcn_rcpf(1.f + __builtin_amdgcn_exp2f(-1.4426950408889634f * z)); }
;   __device__ __forceinline__ void operator()(const Acc& acc, const GUnit& u, int wr, int wc, int fr, int fq) const {
;     ...
;           const u32x2 zw = *(const u32x2*)(Z + off + bj * 128);
;           typedef float f32x2v __attribute__((ext_vector_type(2)));
;           const f32x2v z0 = __builtin_amdgcn_cvt_pk_f32_fp8(zw[0], false), z1 = __builtin_amdgcn_cvt_pk_f32_fp8(zw[0], true), z2 = __builtin_amdgcn_cvt_pk_f32_fp8(zw[1], false), z3 = __builtin_amdgcn_cvt_pk_f32_fp8(zw[1], true);
;           f32x4 a = acc[ai][bj][m][0] * osc, b = acc[ai][bj][m][1] * osc;
;           a[0] *= silu_fast(z0[0]); a[1] *= silu_fast(z0[1]); a[2] *= silu_fast(z1[0]); a[3] *= silu_fast(z1[1]);
;           b[0] *= silu_fast(z2[0]); b[1] *= silu_fast(z2[1]); b[2] *= silu_fast(z3[0]); b[3] *= silu_fast(z3[1]);
;           u32x2 w; w[0] = __builtin_amdgcn_cvt_pk_fp8_f32(a[0], a[1], 0, false); w[0] = __builtin_amdgcn_cvt_pk_fp8_f32(a[2], a[3], w[0], true);
;           w[1] = __builtin_amdgcn_cvt_pk_fp8_f32(b[0], b[1], 0, false); w[1] = __builtin_amdgcn_cvt_pk_fp8_f32(b[2], b[3], w[1], true);
;           *(u32x2*)(Y + off + bj * 128) = w;
	v_cvt_pk_f32_fp8_e32 v[78:79], v226
	v_cvt_pk_f32_fp8_sdwa v[88:89], v226 src0_sel:WORD_1
	v_cvt_pk_f32_fp8_e32 v[90:91], v227
	v_cvt_pk_f32_fp8_sdwa v[76:77], v227 src0_sel:WORD_1
	v_mul_f32_e32 v92, 0xbfb8aa3b, v78
	v_exp_f32_e32 v92, v92
	v_mul_f32_e32 v93, 0xbfb8aa3b, v79
	v_exp_f32_e32 v93, v93
	v_add_f32_e32 v92, 1.0, v92
	v_rcp_f32_e32 v92, v92
	s_nop 0
	v_mul_f32_e32 v78, v78, v92
	v_mul_f32_e32 v60, v60, v78
	v_add_f32_e32 v78, 1.0, v93
	v_mul_f32_e32 v92, 0xbfb8aa3b, v88
	v_rcp_f32_e32 v78, v78
	v_exp_f32_e32 v92, v92
	v_mul_f32_e32 v93, 0xbfb8aa3b, v89
	v_exp_f32_e32 v93, v93
	v_mul_f32_e32 v78, v79, v78
	v_add_f32_e32 v79, 1.0, v92
	v_rcp_f32_e32 v79, v79
	v_add_f32_e32 v92, 1.0, v93
	v_rcp_f32_e32 v92, v92
	v_mul_f32_e32 v61, v61, v78
	v_mul_f32_e32 v78, v88, v79
	v_mul_f32_e32 v79, 0xbfb8aa3b, v90
	v_exp_f32_e32 v79, v79
	v_mul_f32_e32 v88, 0xbfb8aa3b, v91
	v_exp_f32_e32 v88, v88
	v_mul_f32_e32 v62, v62, v78
	v_mul_f32_e32 v78, v89, v92
	v_mul_f32_e32 v63, v63, v78
	v_add_f32_e32 v78, 1.0, v79
	v_rcp_f32_e32 v78, v78
	v_add_f32_e32 v79, 1.0, v88
	v_mul_f32_e32 v88, 0xbfb8aa3b, v76
	v_rcp_f32_e32 v79, v79
	v_exp_f32_e32 v88, v88
	v_mul_f32_e32 v78, v90, v78
	v_mul_f32_e32 v78, v56, v78
	v_mul_f32_e32 v56, v91, v79
	v_add_f32_e32 v79, 1.0, v88
	v_rcp_f32_e32 v79, v79
	v_mul_f32_e32 v88, 0xbfb8aa3b, v77
	v_exp_f32_e32 v88, v88
	v_mul_f32_e32 v89, v57, v56
	v_mul_f32_e32 v56, v76, v79
	v_mul_f32_e32 v58, v58, v56
	v_add_f32_e32 v56, 1.0, v88
	v_rcp_f32_e32 v76, v56
	v_mov_b32_e32 v57, 0
	v_cvt_pk_fp8_f32 v57, v78, v89
	v_mov_b32_e32 v56, 0
	v_cvt_pk_fp8_f32 v56, v60, v61
	v_mul_f32_e32 v60, v77, v76
	v_mul_f32_e32 v59, v59, v60
	v_cvt_pk_fp8_f32 v57, v58, v59 op_sel:[0,0,1]
	v_cvt_pk_f32_fp8_e32 v[58:59], v228
	v_pk_mul_f32 v[78:79], v[84:85], s[12:13] op_sel_hi:[1,0]
	v_cvt_pk_f32_fp8_sdwa v[60:61], v228 src0_sel:WORD_1
	v_cvt_pk_fp8_f32 v56, v62, v63 op_sel:[0,0,1]
	v_mul_f32_e32 v76, 0xbfb8aa3b, v58
	v_exp_f32_e32 v88, v76
	v_mul_f32_e32 v85, 0xbfb8aa3b, v59
	v_exp_f32_e32 v85, v85
	v_cvt_pk_f32_fp8_e32 v[62:63], v229
	v_add_f32_e32 v84, 1.0, v88
	v_rcp_f32_e32 v84, v84
	v_pk_mul_f32 v[76:77], v[86:87], s[12:13] op_sel_hi:[1,0]
	v_cvt_pk_f32_fp8_sdwa v[74:75], v229 src0_sel:WORD_1
	v_mul_f32_e32 v58, v58, v84
	v_mul_f32_e32 v78, v78, v58
	v_add_f32_e32 v58, 1.0, v85
	v_mul_f32_e32 v84, 0xbfb8aa3b, v60
	v_rcp_f32_e32 v58, v58
	v_exp_f32_e32 v84, v84
	v_mul_f32_e32 v85, 0xbfb8aa3b, v61
	v_exp_f32_e32 v85, v85
	v_mul_f32_e32 v58, v59, v58
	v_add_f32_e32 v59, 1.0, v84
	v_rcp_f32_e32 v59, v59
	v_add_f32_e32 v84, 1.0, v85
	v_rcp_f32_e32 v84, v84
	v_mul_f32_e32 v79, v79, v58
	v_mul_f32_e32 v58, v60, v59
	v_mul_f32_e32 v59, 0xbfb8aa3b, v62
	v_mul_f32_e32 v60, v76, v58
	v_mul_f32_e32 v58, v61, v84
	v_exp_f32_e32 v59, v59
	v_mul_f32_e32 v61, 0xbfb8aa3b, v63
	v_exp_f32_e32 v61, v61
	v_mul_f32_e32 v76, v77, v58
	v_add_f32_e32 v58, 1.0, v59
	v_rcp_f32_e32 v58, v58
	v_add_f32_e32 v59, 1.0, v61
	v_mul_f32_e32 v61, 0xbfb8aa3b, v74
	v_rcp_f32_e32 v59, v59
	v_exp_f32_e32 v61, v61
	v_mul_f32_e32 v58, v62, v58
	v_mul_f32_e32 v62, v80, v58
	v_mul_f32_e32 v58, v63, v59
	v_add_f32_e32 v59, 1.0, v61
	v_rcp_f32_e32 v59, v59
	v_mul_f32_e32 v61, 0xbfb8aa3b, v75
	v_exp_f32_e32 v61, v61
	v_mul_f32_e32 v63, v81, v58
	v_mul_f32_e32 v58, v74, v59
	v_mul_f32_e32 v74, v82, v58
	v_add_f32_e32 v58, 1.0, v61
	v_rcp_f32_e32 v61, v58
	v_mov_b32_e32 v58, 0
	v_mov_b32_e32 v59, 0
	v_cvt_pk_fp8_f32 v58, v78, v79
	v_cvt_pk_fp8_f32 v59, v62, v63
	v_mul_f32_e32 v61, v75, v61
	v_mul_f32_e32 v61, v83, v61
	v_cvt_pk_fp8_f32 v58, v60, v76 op_sel:[0,0,1]
	v_cvt_pk_fp8_f32 v59, v74, v61 op_sel:[0,0,1]
	v_lshl_add_u64 v[60:61], s[38:39], 0, v[72:73]
	global_store_dwordx2 v[60:61], v[56:57], off
	global_store_dwordx2 v[60:61], v[58:59], off offset:128
	v_lshl_add_u64 v[56:57], v[132:133], 0, s[8:9]
	v_lshl_add_u64 v[58:59], s[30:31], 0, v[56:57]
	s_nop 0
	s_waitcnt vmcnt(14)
	v_cvt_pk_f32_fp8_e32 v[62:63], v230
	v_cvt_pk_f32_fp8_sdwa v[72:73], v230 src0_sel:WORD_1
	v_cvt_pk_f32_fp8_e32 v[74:75], v231
	v_cvt_pk_f32_fp8_sdwa v[60:61], v231 src0_sel:WORD_1
	v_mul_f32_e32 v76, 0xbfb8aa3b, v62
	v_exp_f32_e32 v76, v76
	v_mul_f32_e32 v77, 0xbfb8aa3b, v63
	v_exp_f32_e32 v77, v77
	v_add_f32_e32 v76, 1.0, v76
	v_rcp_f32_e32 v76, v76
	s_nop 0
	v_mul_f32_e32 v62, v62, v76
	v_mul_f32_e32 v44, v44, v62
	v_add_f32_e32 v62, 1.0, v77
	v_mul_f32_e32 v76, 0xbfb8aa3b, v72
	v_rcp_f32_e32 v62, v62
	v_exp_f32_e32 v76, v76
	v_mul_f32_e32 v77, 0xbfb8aa3b, v73
	v_exp_f32_e32 v77, v77
	v_mul_f32_e32 v62, v63, v62
	v_add_f32_e32 v63, 1.0, v76
	v_rcp_f32_e32 v63, v63
	v_add_f32_e32 v76, 1.0, v77
	v_rcp_f32_e32 v76, v76
	v_mul_f32_e32 v45, v45, v62
	v_mul_f32_e32 v62, v72, v63
	v_mul_f32_e32 v63, 0xbfb8aa3b, v74
	v_exp_f32_e32 v63, v63
	v_mul_f32_e32 v72, 0xbfb8aa3b, v75
	v_exp_f32_e32 v72, v72
	v_mul_f32_e32 v46, v46, v62
	v_mul_f32_e32 v62, v73, v76
	v_mul_f32_e32 v47, v47, v62
	v_add_f32_e32 v62, 1.0, v63
	v_rcp_f32_e32 v62, v62
	v_add_f32_e32 v63, 1.0, v72
	v_mul_f32_e32 v72, 0xbfb8aa3b, v60
	v_rcp_f32_e32 v63, v63
	v_exp_f32_e32 v72, v72
	v_mul_f32_e32 v62, v74, v62
	v_mul_f32_e32 v62, v40, v62
	v_mul_f32_e32 v40, v75, v63
	v_add_f32_e32 v63, 1.0, v72
	v_rcp_f32_e32 v63, v63
	v_mul_f32_e32 v72, 0xbfb8aa3b, v61
	v_exp_f32_e32 v72, v72
	v_mul_f32_e32 v73, v41, v40
	v_mul_f32_e32 v40, v60, v63
	v_mul_f32_e32 v42, v42, v40
	v_add_f32_e32 v40, 1.0, v72
	v_rcp_f32_e32 v60, v40
	v_mov_b32_e32 v41, 0
	v_cvt_pk_fp8_f32 v41, v62, v73
	v_mov_b32_e32 v40, 0
	v_cvt_pk_fp8_f32 v40, v44, v45
	v_mul_f32_e32 v44, v61, v60
	v_mul_f32_e32 v43, v43, v44
	v_cvt_pk_fp8_f32 v41, v42, v43 op_sel:[0,0,1]
; __device__ __forceinline__ float silu_fast(float z) { return z * __builtin_amdgcn_rcpf(1.f + __builtin_amdgcn_exp2f(-1.4426950408889634f * z)); }
;   __device__ __forceinline__ void operator()(const Acc& acc, const GUnit& u, int wr, int wc, int fr, int fq) const {
;     ...
;           const u32x2 zw = *(const u32x2*)(Z + off + bj * 128);
;           typedef float f32x2v __attribute__((ext_vector_type(2)));
;           const f32x2v z0 = __builtin_amdgcn_cvt_pk_f32_fp8(zw[0], false), z1 = __builtin_amdgcn_cvt_pk_f32_fp8(zw[0], true), z2 = __builtin_amdgcn_cvt_pk_f32_fp8(zw[1], false), z3 = __builtin_amdgcn_cvt_pk_f32_fp8(zw[1], true);
;           f32x4 a = acc[ai][bj][m][0] * osc, b = acc[ai][bj][m][1] * osc;
;           a[0] *= silu_fast(z0[0]); a[1] *= silu_fast(z0[1]); a[2] *= silu_fast(z1[0]); a[3] *= silu_fast(z1[1]);
;           b[0] *= silu_fast(z2[0]); b[1] *= silu_fast(z2[1]); b[2] *= silu_fast(z3[0]); b[3] *= silu_fast(z3[1]);
;           u32x2 w; w[0] = __builtin_amdgcn_cvt_pk_fp8_f32(a[0], a[1], 0, false); w[0] = __builtin_amdgcn_cvt_pk_fp8_f32(a[2], a[3], w[0], true);
;           w[1] = __builtin_amdgcn_cvt_pk_fp8_f32(b[0], b[1], 0, false); w[1] = __builtin_amdgcn_cvt_pk_fp8_f32(b[2], b[3], w[1], true);
;           *(u32x2*)(Y + off + bj * 128) = w;
	v_cvt_pk_f32_fp8_e32 v[42:43], v232
	v_pk_mul_f32 v[62:63], v[68:69], s[12:13] op_sel_hi:[1,0]
	v_cvt_pk_f32_fp8_sdwa v[44:45], v232 src0_sel:WORD_1
	v_cvt_pk_fp8_f32 v40, v46, v47 op_sel:[0,0,1]
	v_mul_f32_e32 v60, 0xbfb8aa3b, v42
	v_exp_f32_e32 v72, v60
	v_mul_f32_e32 v69, 0xbfb8aa3b, v43
	v_exp_f32_e32 v69, v69
	v_cvt_pk_f32_fp8_e32 v[46:47], v233
	v_add_f32_e32 v68, 1.0, v72
	v_rcp_f32_e32 v68, v68
	v_pk_mul_f32 v[60:61], v[70:71], s[12:13] op_sel_hi:[1,0]
	v_cvt_pk_f32_fp8_sdwa v[58:59], v233 src0_sel:WORD_1
	v_mul_f32_e32 v42, v42, v68
	v_mul_f32_e32 v62, v62, v42
	v_add_f32_e32 v42, 1.0, v69
	v_mul_f32_e32 v68, 0xbfb8aa3b, v44
	v_rcp_f32_e32 v42, v42
	v_exp_f32_e32 v68, v68
	v_mul_f32_e32 v69, 0xbfb8aa3b, v45
	v_exp_f32_e32 v69, v69
	v_mul_f32_e32 v42, v43, v42
	v_add_f32_e32 v43, 1.0, v68
	v_rcp_f32_e32 v43, v43
	v_add_f32_e32 v68, 1.0, v69
	v_rcp_f32_e32 v68, v68
	v_mul_f32_e32 v63, v63, v42
	v_mul_f32_e32 v42, v44, v43
	v_mul_f32_e32 v43, 0xbfb8aa3b, v46
	v_mul_f32_e32 v44, v60, v42
	v_mul_f32_e32 v42, v45, v68
	v_exp_f32_e32 v43, v43
	v_mul_f32_e32 v45, 0xbfb8aa3b, v47
	v_exp_f32_e32 v45, v45
	v_mul_f32_e32 v60, v61, v42
	v_add_f32_e32 v42, 1.0, v43
	v_rcp_f32_e32 v42, v42
	v_add_f32_e32 v43, 1.0, v45
	v_mul_f32_e32 v45, 0xbfb8aa3b, v58
	v_rcp_f32_e32 v43, v43
	v_exp_f32_e32 v45, v45
	v_mul_f32_e32 v42, v46, v42
	v_mul_f32_e32 v46, v64, v42
	v_mul_f32_e32 v42, v47, v43
	v_add_f32_e32 v43, 1.0, v45
	v_rcp_f32_e32 v43, v43
	v_mul_f32_e32 v45, 0xbfb8aa3b, v59
	v_exp_f32_e32 v45, v45
	v_mul_f32_e32 v47, v65, v42
	v_mul_f32_e32 v42, v58, v43
	v_mul_f32_e32 v58, v66, v42
	v_add_f32_e32 v42, 1.0, v45
	v_rcp_f32_e32 v45, v42
	v_mov_b32_e32 v42, 0
	v_mov_b32_e32 v43, 0
	v_cvt_pk_fp8_f32 v42, v62, v63
	v_cvt_pk_fp8_f32 v43, v46, v47
	v_mul_f32_e32 v45, v59, v45
	v_mul_f32_e32 v45, v67, v45
	v_cvt_pk_fp8_f32 v42, v44, v60 op_sel:[0,0,1]
	v_cvt_pk_fp8_f32 v43, v58, v45 op_sel:[0,0,1]
	v_lshl_add_u64 v[44:45], s[38:39], 0, v[56:57]
	global_store_dwordx2 v[44:45], v[40:41], off
	global_store_dwordx2 v[44:45], v[42:43], off offset:128
	v_lshl_add_u64 v[40:41], v[132:133], 0, s[14:15]
	v_lshl_add_u64 v[42:43], s[30:31], 0, v[40:41]
	s_nop 0
	s_waitcnt vmcnt(14)
	v_cvt_pk_f32_fp8_e32 v[46:47], v234
	v_cvt_pk_f32_fp8_sdwa v[56:57], v234 src0_sel:WORD_1
	v_cvt_pk_f32_fp8_e32 v[58:59], v235
	v_cvt_pk_f32_fp8_sdwa v[44:45], v235 src0_sel:WORD_1
	v_mul_f32_e32 v60, 0xbfb8aa3b, v46
	v_exp_f32_e32 v60, v60
	v_mul_f32_e32 v61, 0xbfb8aa3b, v47
	v_exp_f32_e32 v61, v61
	v_add_f32_e32 v60, 1.0, v60
	v_rcp_f32_e32 v60, v60
	s_nop 0
	v_mul_f32_e32 v46, v46, v60
	v_mul_f32_e32 v28, v28, v46
	v_add_f32_e32 v46, 1.0, v61
	v_mul_f32_e32 v60, 0xbfb8aa3b, v56
	v_rcp_f32_e32 v46, v46
	v_exp_f32_e32 v60, v60
	v_mul_f32_e32 v61, 0xbfb8aa3b, v57
	v_exp_f32_e32 v61, v61
	v_mul_f32_e32 v46, v47, v46
	v_add_f32_e32 v47, 1.0, v60
	v_rcp_f32_e32 v47, v47
	v_add_f32_e32 v60, 1.0, v61
	v_rcp_f32_e32 v60, v60
	v_mul_f32_e32 v29, v29, v46
	v_mul_f32_e32 v46, v56, v47
	v_mul_f32_e32 v47, 0xbfb8aa3b, v58
	v_exp_f32_e32 v47, v47
	v_mul_f32_e32 v56, 0xbfb8aa3b, v59
	v_exp_f32_e32 v56, v56
	v_mul_f32_e32 v30, v30, v46
	v_mul_f32_e32 v46, v57, v60
	v_mul_f32_e32 v31, v31, v46
	v_add_f32_e32 v46, 1.0, v47
	v_rcp_f32_e32 v46, v46
	v_add_f32_e32 v47, 1.0, v56
	v_mul_f32_e32 v56, 0xbfb8aa3b, v44
	v_rcp_f32_e32 v47, v47
	v_exp_f32_e32 v56, v56
	v_mul_f32_e32 v46, v58, v46
	v_mul_f32_e32 v46, v24, v46
	v_mul_f32_e32 v24, v59, v47
	v_add_f32_e32 v47, 1.0, v56
	v_rcp_f32_e32 v47, v47
	v_mul_f32_e32 v56, 0xbfb8aa3b, v45
	v_exp_f32_e32 v56, v56
	v_mul_f32_e32 v57, v25, v24
	v_mul_f32_e32 v24, v44, v47
	v_mul_f32_e32 v26, v26, v24
	v_add_f32_e32 v24, 1.0, v56
	v_rcp_f32_e32 v44, v24
	v_mov_b32_e32 v25, 0
	v_cvt_pk_fp8_f32 v25, v46, v57
	v_mov_b32_e32 v24, 0
	v_cvt_pk_fp8_f32 v24, v28, v29
	v_mul_f32_e32 v28, v45, v44
	v_mul_f32_e32 v27, v27, v28
	v_cvt_pk_fp8_f32 v25, v26, v27 op_sel:[0,0,1]
	v_cvt_pk_f32_fp8_e32 v[26:27], v236
	v_pk_mul_f32 v[46:47], v[52:53], s[12:13] op_sel_hi:[1,0]
	v_cvt_pk_f32_fp8_sdwa v[28:29], v236 src0_sel:WORD_1
	v_cvt_pk_fp8_f32 v24, v30, v31 op_sel:[0,0,1]
	v_mul_f32_e32 v44, 0xbfb8aa3b, v26
	v_exp_f32_e32 v56, v44
	v_mul_f32_e32 v53, 0xbfb8aa3b, v27
	v_exp_f32_e32 v53, v53
	v_cvt_pk_f32_fp8_e32 v[30:31], v237
	v_add_f32_e32 v52, 1.0, v56
	v_rcp_f32_e32 v52, v52
	v_pk_mul_f32 v[44:45], v[54:55], s[12:13] op_sel_hi:[1,0]
	v_cvt_pk_f32_fp8_sdwa v[42:43], v237 src0_sel:WORD_1
	v_mul_f32_e32 v26, v26, v52
	v_mul_f32_e32 v46, v46, v26
	v_add_f32_e32 v26, 1.0, v53
	v_mul_f32_e32 v52, 0xbfb8aa3b, v28
	v_rcp_f32_e32 v26, v26
	v_exp_f32_e32 v52, v52
	v_mul_f32_e32 v53, 0xbfb8aa3b, v29
	v_exp_f32_e32 v53, v53
	v_mul_f32_e32 v26, v27, v26
	v_add_f32_e32 v27, 1.0, v52
	v_rcp_f32_e32 v27, v27
	v_add_f32_e32 v52, 1.0, v53
	v_rcp_f32_e32 v52, v52
	v_mul_f32_e32 v47, v47, v26
	v_mul_f32_e32 v26, v28, v27
	v_mul_f32_e32 v27, 0xbfb8aa3b, v30
	v_mul_f32_e32 v28, v44, v26
	v_mul_f32_e32 v26, v29, v52
	v_exp_f32_e32 v27, v27
	v_mul_f32_e32 v29, 0xbfb8aa3b, v31
	v_exp_f32_e32 v29, v29
	v_mul_f32_e32 v44, v45, v26
	v_add_f32_e32 v26, 1.0, v27
	v_rcp_f32_e32 v26, v26
	v_add_f32_e32 v27, 1.0, v29
	v_mul_f32_e32 v29, 0xbfb8aa3b, v42
	v_rcp_f32_e32 v27, v27
	v_exp_f32_e32 v29, v29
	v_mul_f32_e32 v26, v30, v26
	v_mul_f32_e32 v30, v48, v26
	v_mul_f32_e32 v26, v31, v27
	v_add_f32_e32 v27, 1.0, v29
	v_rcp_f32_e32 v27, v27
	v_mul_f32_e32 v29, 0xbfb8aa3b, v43
	v_exp_f32_e32 v29, v29
	v_mul_f32_e32 v31, v49, v26
	v_mul_f32_e32 v26, v42, v27
	v_mul_f32_e32 v42, v50, v26
	v_add_f32_e32 v26, 1.0, v29
	v_rcp_f32_e32 v29, v26
	v_mov_b32_e32 v26, 0
	v_mov_b32_e32 v27, 0
	v_cvt_pk_fp8_f32 v26, v46, v47
	v_cvt_pk_fp8_f32 v27, v30, v31
	v_mul_f32_e32 v29, v43, v29
	v_mul_f32_e32 v29, v51, v29
	v_cvt_pk_fp8_f32 v26, v28, v44 op_sel:[0,0,1]
	v_cvt_pk_fp8_f32 v27, v42, v29 op_sel:[0,0,1]
	v_lshl_add_u64 v[28:29], s[38:39], 0, v[40:41]
	global_store_dwordx2 v[28:29], v[24:25], off
	global_store_dwordx2 v[28:29], v[26:27], off offset:128
	v_lshl_add_u64 v[24:25], v[132:133], 0, s[16:17]
	v_lshl_add_u64 v[26:27], s[30:31], 0, v[24:25]
	s_nop 0
	s_waitcnt vmcnt(14)
; __device__ __forceinline__ float silu_fast(float z) { return z * __builtin_amdgcn_rcpf(1.f + __builtin_amdgcn_exp2f(-1.4426950408889634f * z)); }
;   __device__ __forceinline__ void operator()(const Acc& acc, const GUnit& u, int wr, int wc, int fr, int fq) const {
;     ...
;           const u32x2 zw = *(const u32x2*)(Z + off + bj * 128);
;           typedef float f32x2v __attribute__((ext_vector_type(2)));
;           const f32x2v z0 = __builtin_amdgcn_cvt_pk_f32_fp8(zw[0], false), z1 = __builtin_amdgcn_cvt_pk_f32_fp8(zw[0], true), z2 = __builtin_amdgcn_cvt_pk_f32_fp8(zw[1], false), z3 = __builtin_amdgcn_cvt_pk_f32_fp8(zw[1], true);
;           f32x4 a = acc[ai][bj][m][0] * osc, b = acc[ai][bj][m][1] * osc;
;           a[0] *= silu_fast(z0[0]); a[1] *= silu_fast(z0[1]); a[2] *= silu_fast(z1[0]); a[3] *= silu_fast(z1[1]);
;           b[0] *= silu_fast(z2[0]); b[1] *= silu_fast(z2[1]); b[2] *= silu_fast(z3[0]); b[3] *= silu_fast(z3[1]);
;           u32x2 w; w[0] = __builtin_amdgcn_cvt_pk_fp8_f32(a[0], a[1], 0, false); w[0] = __builtin_amdgcn_cvt_pk_fp8_f32(a[2], a[3], w[0], true);
;           w[1] = __builtin_amdgcn_cvt_pk_fp8_f32(b[0], b[1], 0, false); w[1] = __builtin_amdgcn_cvt_pk_fp8_f32(b[2], b[3], w[1], true);
;           *(u32x2*)(Y + off + bj * 128) = w;
	v_cvt_pk_f32_fp8_e32 v[30:31], v238
	v_cvt_pk_f32_fp8_sdwa v[40:41], v238 src0_sel:WORD_1
	v_cvt_pk_f32_fp8_e32 v[42:43], v239
	v_cvt_pk_f32_fp8_sdwa v[28:29], v239 src0_sel:WORD_1
	v_mul_f32_e32 v44, 0xbfb8aa3b, v30
	v_exp_f32_e32 v44, v44
	v_mul_f32_e32 v45, 0xbfb8aa3b, v31
	v_exp_f32_e32 v45, v45
	v_add_f32_e32 v44, 1.0, v44
	v_rcp_f32_e32 v44, v44
	s_nop 0
	v_mul_f32_e32 v30, v30, v44
	v_mul_f32_e32 v12, v12, v30
	v_add_f32_e32 v30, 1.0, v45
	v_mul_f32_e32 v44, 0xbfb8aa3b, v40
	v_rcp_f32_e32 v30, v30
	v_exp_f32_e32 v44, v44
	v_mul_f32_e32 v45, 0xbfb8aa3b, v41
	v_exp_f32_e32 v45, v45
	v_mul_f32_e32 v30, v31, v30
	v_add_f32_e32 v31, 1.0, v44
	v_rcp_f32_e32 v31, v31
	v_add_f32_e32 v44, 1.0, v45
	v_rcp_f32_e32 v44, v44
	v_mul_f32_e32 v13, v13, v30
	v_mul_f32_e32 v30, v40, v31
	v_mul_f32_e32 v31, 0xbfb8aa3b, v42
	v_exp_f32_e32 v31, v31
	v_mul_f32_e32 v40, 0xbfb8aa3b, v43
	v_exp_f32_e32 v40, v40
	v_mul_f32_e32 v14, v14, v30
	v_mul_f32_e32 v30, v41, v44
	v_mul_f32_e32 v15, v15, v30
	v_add_f32_e32 v30, 1.0, v31
	v_rcp_f32_e32 v30, v30
	v_add_f32_e32 v31, 1.0, v40
	v_mul_f32_e32 v40, 0xbfb8aa3b, v28
	v_rcp_f32_e32 v31, v31
	v_exp_f32_e32 v40, v40
	v_mul_f32_e32 v30, v42, v30
	v_mul_f32_e32 v30, v8, v30
	v_mul_f32_e32 v8, v43, v31
	v_add_f32_e32 v31, 1.0, v40
	v_rcp_f32_e32 v31, v31
	v_mul_f32_e32 v40, 0xbfb8aa3b, v29
	v_exp_f32_e32 v40, v40
	v_mul_f32_e32 v41, v9, v8
	v_mul_f32_e32 v8, v28, v31
	v_mul_f32_e32 v10, v10, v8
	v_add_f32_e32 v8, 1.0, v40
	v_rcp_f32_e32 v28, v8
	v_mov_b32_e32 v9, 0
	v_cvt_pk_fp8_f32 v9, v30, v41
	v_mov_b32_e32 v8, 0
	v_cvt_pk_fp8_f32 v8, v12, v13
	v_mul_f32_e32 v12, v29, v28
	v_mul_f32_e32 v11, v11, v12
	v_cvt_pk_fp8_f32 v9, v10, v11 op_sel:[0,0,1]
	v_cvt_pk_f32_fp8_e32 v[10:11], v240
	v_pk_mul_f32 v[30:31], v[36:37], s[12:13] op_sel_hi:[1,0]
	v_cvt_pk_f32_fp8_sdwa v[12:13], v240 src0_sel:WORD_1
	v_cvt_pk_fp8_f32 v8, v14, v15 op_sel:[0,0,1]
	v_mul_f32_e32 v28, 0xbfb8aa3b, v10
	v_exp_f32_e32 v40, v28
	v_mul_f32_e32 v37, 0xbfb8aa3b, v11
	v_exp_f32_e32 v37, v37
	v_cvt_pk_f32_fp8_e32 v[14:15], v241
	v_add_f32_e32 v36, 1.0, v40
	v_rcp_f32_e32 v36, v36
	v_pk_mul_f32 v[28:29], v[38:39], s[12:13] op_sel_hi:[1,0]
	v_cvt_pk_f32_fp8_sdwa v[26:27], v241 src0_sel:WORD_1
	v_mul_f32_e32 v10, v10, v36
	v_mul_f32_e32 v30, v30, v10
	v_add_f32_e32 v10, 1.0, v37
	v_mul_f32_e32 v36, 0xbfb8aa3b, v12
	v_rcp_f32_e32 v10, v10
	v_exp_f32_e32 v36, v36
	v_mul_f32_e32 v37, 0xbfb8aa3b, v13
	v_exp_f32_e32 v37, v37
	v_mul_f32_e32 v10, v11, v10
	v_add_f32_e32 v11, 1.0, v36
	v_rcp_f32_e32 v11, v11
	v_add_f32_e32 v36, 1.0, v37
	v_rcp_f32_e32 v36, v36
	v_mul_f32_e32 v31, v31, v10
	v_mul_f32_e32 v10, v12, v11
	v_mul_f32_e32 v11, 0xbfb8aa3b, v14
	v_mul_f32_e32 v12, v28, v10
	v_mul_f32_e32 v10, v13, v36
	v_exp_f32_e32 v11, v11
	v_mul_f32_e32 v13, 0xbfb8aa3b, v15
	v_exp_f32_e32 v13, v13
	v_mul_f32_e32 v28, v29, v10
	v_add_f32_e32 v10, 1.0, v11
	v_rcp_f32_e32 v10, v10
	v_add_f32_e32 v11, 1.0, v13
	v_mul_f32_e32 v13, 0xbfb8aa3b, v26
	v_rcp_f32_e32 v11, v11
	v_exp_f32_e32 v13, v13
	v_mul_f32_e32 v10, v14, v10
	v_mul_f32_e32 v14, v32, v10
	v_mul_f32_e32 v10, v15, v11
	v_add_f32_e32 v11, 1.0, v13
	v_rcp_f32_e32 v11, v11
	v_mul_f32_e32 v13, 0xbfb8aa3b, v27
	v_exp_f32_e32 v13, v13
	v_mul_f32_e32 v15, v33, v10
	v_mul_f32_e32 v10, v26, v11
	v_mul_f32_e32 v26, v34, v10
	v_add_f32_e32 v10, 1.0, v13
	v_rcp_f32_e32 v13, v10
	v_mov_b32_e32 v10, 0
	v_mov_b32_e32 v11, 0
	v_cvt_pk_fp8_f32 v10, v30, v31
	v_cvt_pk_fp8_f32 v11, v14, v15
	v_mul_f32_e32 v13, v27, v13
	v_mul_f32_e32 v13, v35, v13
	v_cvt_pk_fp8_f32 v10, v12, v28 op_sel:[0,0,1]
	v_cvt_pk_fp8_f32 v11, v26, v13 op_sel:[0,0,1]
	v_lshl_add_u64 v[12:13], s[38:39], 0, v[24:25]
	global_store_dwordx2 v[12:13], v[8:9], off
	global_store_dwordx2 v[12:13], v[10:11], off offset:128
	v_lshl_add_u64 v[8:9], v[132:133], 0, s[18:19]
	v_lshl_add_u64 v[10:11], s[30:31], 0, v[8:9]
	s_nop 0
	s_waitcnt vmcnt(14)
; __device__ __forceinline__ float silu_fast(float z) { return z * __builtin_amdgcn_rcpf(1.f + __builtin_amdgcn_exp2f(-1.4426950408889634f * z)); }
; #define G8_BAR __builtin_amdgcn_s_barrier()
;     ...
;     if (!has_next) break;
; #pragma unroll
;     for (int a = 0; a < 2; ++a)
; #pragma unroll
;       for (int b = 0; b < 2; ++b)
; #pragma unroll
;         for (int m = 0; m < 4; ++m)
; #pragma unroll
;           for (int n = 0; n < 2; ++n) acc[a][b][m][n] = (f32x4){0.f, 0.f, 0.f, 0.f};
;     cur = nxt; cA = nA; cB = nB; ++ui;
;     if (wr == 1) G8_BAR;
;   __device__ __forceinline__ void operator()(const Acc& acc, const GUnit& u, int wr, int wc, int fr, int fq) const {
;     ...
;           const u32x2 zw = *(const u32x2*)(Z + off + bj * 128);
;           typedef float f32x2v __attribute__((ext_vector_type(2)));
;           const f32x2v z0 = __builtin_amdgcn_cvt_pk_f32_fp8(zw[0], false), z1 = __builtin_amdgcn_cvt_pk_f32_fp8(zw[0], true), z2 = __builtin_amdgcn_cvt_pk_f32_fp8(zw[1], false), z3 = __builtin_amdgcn_cvt_pk_f32_fp8(zw[1], true);
;           f32x4 a = acc[ai][bj][m][0] * osc, b = acc[ai][bj][m][1] * osc;
;           a[0] *= silu_fast(z0[0]); a[1] *= silu_fast(z0[1]); a[2] *= silu_fast(z1[0]); a[3] *= silu_fast(z1[1]);
;           b[0] *= silu_fast(z2[0]); b[1] *= silu_fast(z2[1]); b[2] *= silu_fast(z3[0]); b[3] *= silu_fast(z3[1]);
;           u32x2 w; w[0] = __builtin_amdgcn_cvt_pk_fp8_f32(a[0], a[1], 0, false); w[0] = __builtin_amdgcn_cvt_pk_fp8_f32(a[2], a[3], w[0], true);
;           w[1] = __builtin_amdgcn_cvt_pk_fp8_f32(b[0], b[1], 0, false); w[1] = __builtin_amdgcn_cvt_pk_fp8_f32(b[2], b[3], w[1], true);
;           *(u32x2*)(Y + off + bj * 128) = w;
	v_cvt_pk_f32_fp8_e32 v[14:15], v242
	v_cvt_pk_f32_fp8_sdwa v[24:25], v242 src0_sel:WORD_1
	v_cvt_pk_f32_fp8_e32 v[26:27], v243
	v_cvt_pk_f32_fp8_sdwa v[12:13], v243 src0_sel:WORD_1
	v_mul_f32_e32 v28, 0xbfb8aa3b, v14
	v_exp_f32_e32 v28, v28
	v_mul_f32_e32 v29, 0xbfb8aa3b, v15
	v_exp_f32_e32 v29, v29
	v_add_f32_e32 v28, 1.0, v28
	v_rcp_f32_e32 v28, v28
	s_nop 0
	v_mul_f32_e32 v14, v14, v28
	v_mul_f32_e32 v4, v4, v14
	v_add_f32_e32 v14, 1.0, v29
	v_mul_f32_e32 v28, 0xbfb8aa3b, v24
	v_rcp_f32_e32 v14, v14
	v_exp_f32_e32 v28, v28
	v_mul_f32_e32 v29, 0xbfb8aa3b, v25
	v_exp_f32_e32 v29, v29
	v_mul_f32_e32 v14, v15, v14
	v_add_f32_e32 v15, 1.0, v28
	v_rcp_f32_e32 v15, v15
	v_add_f32_e32 v28, 1.0, v29
	v_rcp_f32_e32 v28, v28
	v_mul_f32_e32 v5, v5, v14
	v_mul_f32_e32 v14, v24, v15
	v_mul_f32_e32 v15, 0xbfb8aa3b, v26
	v_exp_f32_e32 v15, v15
	v_mul_f32_e32 v24, 0xbfb8aa3b, v27
	v_exp_f32_e32 v24, v24
	v_mul_f32_e32 v6, v6, v14
	v_mul_f32_e32 v14, v25, v28
	v_mul_f32_e32 v7, v7, v14
	v_add_f32_e32 v14, 1.0, v15
	v_rcp_f32_e32 v14, v14
	v_add_f32_e32 v15, 1.0, v24
	v_mul_f32_e32 v24, 0xbfb8aa3b, v12
	v_rcp_f32_e32 v15, v15
	v_exp_f32_e32 v24, v24
	v_mul_f32_e32 v14, v26, v14
	v_mul_f32_e32 v14, v0, v14
	v_mul_f32_e32 v0, v27, v15
	v_add_f32_e32 v15, 1.0, v24
	v_rcp_f32_e32 v15, v15
	v_mul_f32_e32 v24, 0xbfb8aa3b, v13
	v_exp_f32_e32 v24, v24
	v_mul_f32_e32 v25, v1, v0
	v_mul_f32_e32 v0, v12, v15
	v_mul_f32_e32 v2, v2, v0
	v_add_f32_e32 v0, 1.0, v24
	v_rcp_f32_e32 v12, v0
	v_mov_b32_e32 v1, 0
	v_cvt_pk_fp8_f32 v1, v14, v25
	v_mov_b32_e32 v0, 0
	v_cvt_pk_fp8_f32 v0, v4, v5
	v_mul_f32_e32 v4, v13, v12
	v_mul_f32_e32 v3, v3, v4
	v_cvt_pk_fp8_f32 v1, v2, v3 op_sel:[0,0,1]
	v_cvt_pk_f32_fp8_e32 v[2:3], v244
	v_pk_mul_f32 v[14:15], v[20:21], s[12:13] op_sel_hi:[1,0]
	v_cvt_pk_f32_fp8_sdwa v[4:5], v244 src0_sel:WORD_1
	v_cvt_pk_fp8_f32 v0, v6, v7 op_sel:[0,0,1]
	v_mul_f32_e32 v12, 0xbfb8aa3b, v2
	v_exp_f32_e32 v24, v12
	v_mul_f32_e32 v21, 0xbfb8aa3b, v3
	v_exp_f32_e32 v21, v21
	v_cvt_pk_f32_fp8_e32 v[6:7], v245
	v_add_f32_e32 v20, 1.0, v24
	v_rcp_f32_e32 v20, v20
	v_pk_mul_f32 v[12:13], v[22:23], s[12:13] op_sel_hi:[1,0]
	v_cvt_pk_f32_fp8_sdwa v[10:11], v245 src0_sel:WORD_1
	v_mul_f32_e32 v2, v2, v20
	v_mul_f32_e32 v14, v14, v2
	v_add_f32_e32 v2, 1.0, v21
	v_mul_f32_e32 v20, 0xbfb8aa3b, v4
	v_rcp_f32_e32 v2, v2
	v_exp_f32_e32 v20, v20
	v_mul_f32_e32 v21, 0xbfb8aa3b, v5
	v_exp_f32_e32 v21, v21
	v_mul_f32_e32 v2, v3, v2
	v_add_f32_e32 v3, 1.0, v20
	v_rcp_f32_e32 v3, v3
	v_add_f32_e32 v20, 1.0, v21
	v_rcp_f32_e32 v20, v20
	v_mul_f32_e32 v15, v15, v2
	v_mul_f32_e32 v2, v4, v3
	v_mul_f32_e32 v3, 0xbfb8aa3b, v6
	v_mul_f32_e32 v4, v12, v2
	v_mul_f32_e32 v2, v5, v20
	v_exp_f32_e32 v3, v3
	v_mul_f32_e32 v5, 0xbfb8aa3b, v7
	v_exp_f32_e32 v5, v5
	v_mul_f32_e32 v12, v13, v2
	v_add_f32_e32 v2, 1.0, v3
	v_rcp_f32_e32 v2, v2
	v_add_f32_e32 v3, 1.0, v5
	v_mul_f32_e32 v5, 0xbfb8aa3b, v10
	v_rcp_f32_e32 v3, v3
	v_exp_f32_e32 v5, v5
	v_mul_f32_e32 v2, v6, v2
	v_mul_f32_e32 v6, v16, v2
	v_mul_f32_e32 v2, v7, v3
	v_add_f32_e32 v3, 1.0, v5
	v_rcp_f32_e32 v3, v3
	v_mul_f32_e32 v5, 0xbfb8aa3b, v11
	v_exp_f32_e32 v5, v5
	v_mul_f32_e32 v7, v17, v2
	v_mul_f32_e32 v2, v10, v3
	v_mul_f32_e32 v10, v18, v2
	v_add_f32_e32 v2, 1.0, v5
	v_rcp_f32_e32 v5, v2
	v_mov_b32_e32 v2, 0
	v_mov_b32_e32 v3, 0
	v_cvt_pk_fp8_f32 v2, v14, v15
	v_cvt_pk_fp8_f32 v3, v6, v7
	v_mul_f32_e32 v5, v11, v5
	v_mul_f32_e32 v5, v19, v5
	v_cvt_pk_fp8_f32 v2, v4, v12 op_sel:[0,0,1]
	v_cvt_pk_fp8_f32 v3, v10, v5 op_sel:[0,0,1]
	v_lshl_add_u64 v[4:5], s[38:39], 0, v[8:9]
	global_store_dwordx2 v[4:5], v[0:1], off
	global_store_dwordx2 v[4:5], v[2:3], off offset:128
	s_cbranch_vccnz .LBB0_1037
	s_andn2_b64 vcc, exec, s[4:5]
	s_cbranch_vccnz .LBB0_1036
	s_barrier
	s_branch .LBB0_1036
